# GEMM epilogue sigmoids: 11-instruction IEEE 1/x expansion replaced by one f32 v_rcp_f32 (384 sites), on top of GLA load batching
# speedup vs baseline: 1.0437x; 1.0267x over previous
; DI u32x4 pack8(f32x4 a, f32x4 b) { u32x4 w; w.x = pk2(a[0], a[1]); w.y = pk2(a[2], a[3]); w.z = pk2(b[0], b[1]); w.w = pk2(b[2], b[3]); return w; }
; DI float sigmoidf_(float v) { return __fdividef(1.f, 1.f + __expf(-v)); }
; template <int PH>
; DI void epilogue(const Params& p, const f32x4 (&acc)[2][2][4][2], const Unit& u, int wr, int wc, int fr, int fq) {
;     ...
;                         } else if (kind == K_GATE) {
; #pragma unroll
;                             for (int j = 0; j < 4; ++j) { v0[j] = sigmoidf_(v0[j]); v1[j] = sigmoidf_(v1[j]); }
;                         } else { v0 = v0 * sc; v1 = v1 * sc; }
;                         *(u32x4*)(d + 32 * bj) = pack8(v0, v1);
.LBB0_383:
	s_andn2_b64 vcc, exec, s[6:7]
	s_cbranch_vccnz .LBB0_385
	v_mul_f32_e32 v130, 0xbfb8aa3b, v121
	v_mul_f32_e32 v131, 0xbfb8aa3b, v122
	v_exp_f32_e32 v133, v130
	v_mul_f32_e32 v130, 0xbfb8aa3b, v126
	v_exp_f32_e32 v134, v131
	v_mul_f32_e32 v131, 0xbfb8aa3b, v127
	v_exp_f32_e32 v130, v130
	v_exp_f32_e32 v131, v131
	v_mul_f32_e32 v129, 0xbfb8aa3b, v120
	v_mul_f32_e32 v128, 0xbfb8aa3b, v124
	v_exp_f32_e32 v132, v129
	v_pk_add_f32 v[130:131], v[130:131], 1.0 op_sel_hi:[1,0]
	v_mul_f32_e32 v129, 0xbfb8aa3b, v125
	v_exp_f32_e32 v128, v128
	v_exp_f32_e32 v129, v129
	v_pk_add_f32 v[132:133], v[132:133], 1.0 op_sel_hi:[1,0]
	v_rcp_f32_e32 v131, v131
	v_pk_add_f32 v[128:129], v[128:129], 1.0 op_sel_hi:[1,0]
	v_rcp_f32_e32 v130, v130
	s_nop 0
	v_rcp_f32_e32 v129, v129
	s_nop 0
	v_rcp_f32_e32 v128, v128
	v_mul_f32_e32 v135, 0xbfb8aa3b, v123
	v_exp_f32_e32 v135, v135
	s_nop 0
	v_pk_add_f32 v[134:135], v[134:135], 1.0 op_sel_hi:[1,0]
	s_nop 0
	s_nop 0
	v_rcp_f32_e32 v135, v135
	s_nop 0
	v_rcp_f32_e32 v134, v134
	s_nop 0
	v_rcp_f32_e32 v133, v133
	s_nop 0
	v_rcp_f32_e32 v132, v132

; DI float sigmoidf_(float v) { return __fdividef(1.f, 1.f + __expf(-v)); }
; template <int PH>
; DI void epilogue(const Params& p, const f32x4 (&acc)[2][2][4][2], const Unit& u, int wr, int wc, int fr, int fq) {
;     ...
;                         if (kind == K_SILU) {
; #pragma unroll
;                             for (int j = 0; j < 4; ++j) { v0[j] = v0[j] * sigmoidf_(v0[j]); v1[j] = v1[j] * sigmoidf_(v1[j]); }
.LBB0_386:
	s_andn2_b64 vcc, exec, s[6:7]
	s_cbranch_vccnz .LBB0_388
	v_mul_f32_e32 v129, 0xbfb8aa3b, v120
	v_mul_f32_e32 v128, 0xbfb8aa3b, v124
	v_exp_f32_e32 v132, v129
	v_mul_f32_e32 v129, 0xbfb8aa3b, v125
	v_exp_f32_e32 v128, v128
	v_exp_f32_e32 v129, v129
	v_mul_f32_e32 v130, 0xbfb8aa3b, v121
	v_mul_f32_e32 v131, 0xbfb8aa3b, v122
	v_exp_f32_e32 v133, v130
	v_pk_add_f32 v[128:129], v[128:129], 1.0 op_sel_hi:[1,0]
	v_mul_f32_e32 v130, 0xbfb8aa3b, v126
	v_exp_f32_e32 v134, v131
	v_mul_f32_e32 v131, 0xbfb8aa3b, v127
	v_exp_f32_e32 v130, v130
	v_rcp_f32_e32 v129, v129
	v_exp_f32_e32 v131, v131
	v_pk_add_f32 v[132:133], v[132:133], 1.0 op_sel_hi:[1,0]
	v_pk_add_f32 v[130:131], v[130:131], 1.0 op_sel_hi:[1,0]
	v_rcp_f32_e32 v128, v128
	s_nop 0
	v_pk_mul_f32 v[128:129], v[124:125], v[128:129]
	v_rcp_f32_e32 v131, v131
	s_nop 0
	v_rcp_f32_e32 v130, v130
	v_mul_f32_e32 v135, 0xbfb8aa3b, v123
	v_exp_f32_e32 v135, v135
	v_rcp_f32_e32 v133, v133
	v_pk_add_f32 v[134:135], v[134:135], 1.0 op_sel_hi:[1,0]
	v_pk_mul_f32 v[130:131], v[126:127], v[130:131]
	v_rcp_f32_e32 v132, v132
	s_nop 0
	v_pk_mul_f32 v[132:133], v[120:121], v[132:133]
	v_rcp_f32_e32 v135, v135
	s_nop 0
	v_rcp_f32_e32 v134, v134
	s_nop 0
	v_pk_mul_f32 v[134:135], v[122:123], v[134:135]

; DI u32x4 pack8(f32x4 a, f32x4 b) { u32x4 w; w.x = pk2(a[0], a[1]); w.y = pk2(a[2], a[3]); w.z = pk2(b[0], b[1]); w.w = pk2(b[2], b[3]); return w; }
; DI float sigmoidf_(float v) { return __fdividef(1.f, 1.f + __expf(-v)); }
; template <int PH>
; DI void epilogue(const Params& p, const f32x4 (&acc)[2][2][4][2], const Unit& u, int wr, int wc, int fr, int fq) {
;     ...
;                         } else if (kind == K_GATE) {
; #pragma unroll
;                             for (int j = 0; j < 4; ++j) { v0[j] = sigmoidf_(v0[j]); v1[j] = sigmoidf_(v1[j]); }
;                         } else { v0 = v0 * sc; v1 = v1 * sc; }
;                         *(u32x4*)(d + 32 * bj) = pack8(v0, v1);
.LBB0_391:
	s_andn2_b64 vcc, exec, s[70:71]
	s_cbranch_vccnz .LBB0_393
	v_mul_f32_e32 v130, 0xbfb8aa3b, v89
	v_mul_f32_e32 v131, 0xbfb8aa3b, v90
	v_exp_f32_e32 v133, v130
	v_mul_f32_e32 v130, 0xbfb8aa3b, v94
	v_exp_f32_e32 v134, v131
	v_mul_f32_e32 v131, 0xbfb8aa3b, v95
	v_exp_f32_e32 v130, v130
	v_exp_f32_e32 v131, v131
	v_mul_f32_e32 v129, 0xbfb8aa3b, v88
	v_mul_f32_e32 v128, 0xbfb8aa3b, v92
	v_exp_f32_e32 v132, v129
	v_pk_add_f32 v[130:131], v[130:131], 1.0 op_sel_hi:[1,0]
	v_mul_f32_e32 v129, 0xbfb8aa3b, v93
	v_exp_f32_e32 v128, v128
	v_exp_f32_e32 v129, v129
	v_pk_add_f32 v[132:133], v[132:133], 1.0 op_sel_hi:[1,0]
	v_rcp_f32_e32 v131, v131
	v_pk_add_f32 v[128:129], v[128:129], 1.0 op_sel_hi:[1,0]
	v_rcp_f32_e32 v130, v130
	s_nop 0
	v_rcp_f32_e32 v129, v129
	s_nop 0
	v_rcp_f32_e32 v128, v128
	v_mul_f32_e32 v135, 0xbfb8aa3b, v91
	v_exp_f32_e32 v135, v135
	s_nop 0
	v_pk_add_f32 v[134:135], v[134:135], 1.0 op_sel_hi:[1,0]
	s_nop 0
	s_nop 0
	v_rcp_f32_e32 v135, v135
	s_nop 0
	v_rcp_f32_e32 v134, v134
	s_nop 0
	v_rcp_f32_e32 v133, v133
	s_nop 0
	v_rcp_f32_e32 v132, v132

; DI float sigmoidf_(float v) { return __fdividef(1.f, 1.f + __expf(-v)); }
; template <int PH>
; DI void epilogue(const Params& p, const f32x4 (&acc)[2][2][4][2], const Unit& u, int wr, int wc, int fr, int fq) {
;     ...
;                         if (kind == K_SILU) {
; #pragma unroll
;                             for (int j = 0; j < 4; ++j) { v0[j] = v0[j] * sigmoidf_(v0[j]); v1[j] = v1[j] * sigmoidf_(v1[j]); }
.LBB0_394:
	s_andn2_b64 vcc, exec, s[72:73]
	s_cbranch_vccnz .LBB0_396
	v_mul_f32_e32 v129, 0xbfb8aa3b, v88
	v_mul_f32_e32 v128, 0xbfb8aa3b, v92
	v_exp_f32_e32 v132, v129
	v_mul_f32_e32 v129, 0xbfb8aa3b, v93
	v_exp_f32_e32 v128, v128
	v_exp_f32_e32 v129, v129
	v_mul_f32_e32 v130, 0xbfb8aa3b, v89
	v_mul_f32_e32 v131, 0xbfb8aa3b, v90
	v_exp_f32_e32 v133, v130
	v_pk_add_f32 v[128:129], v[128:129], 1.0 op_sel_hi:[1,0]
	v_mul_f32_e32 v130, 0xbfb8aa3b, v94
	v_exp_f32_e32 v134, v131
	v_mul_f32_e32 v131, 0xbfb8aa3b, v95
	v_exp_f32_e32 v130, v130
	v_rcp_f32_e32 v129, v129
	v_exp_f32_e32 v131, v131
	v_pk_add_f32 v[132:133], v[132:133], 1.0 op_sel_hi:[1,0]
	v_pk_add_f32 v[130:131], v[130:131], 1.0 op_sel_hi:[1,0]
	v_rcp_f32_e32 v128, v128
	s_nop 0
	v_pk_mul_f32 v[128:129], v[92:93], v[128:129]
	v_rcp_f32_e32 v131, v131
	s_nop 0
	v_rcp_f32_e32 v130, v130
	v_mul_f32_e32 v135, 0xbfb8aa3b, v91
	v_exp_f32_e32 v135, v135
	v_rcp_f32_e32 v133, v133
	v_pk_add_f32 v[134:135], v[134:135], 1.0 op_sel_hi:[1,0]
	v_pk_mul_f32 v[130:131], v[94:95], v[130:131]
	v_rcp_f32_e32 v132, v132
	s_nop 0
	v_pk_mul_f32 v[132:133], v[88:89], v[132:133]
	v_rcp_f32_e32 v135, v135
	s_nop 0
	v_rcp_f32_e32 v134, v134
	s_nop 0
	v_pk_mul_f32 v[134:135], v[90:91], v[134:135]

; DI u32x4 pack8(f32x4 a, f32x4 b) { u32x4 w; w.x = pk2(a[0], a[1]); w.y = pk2(a[2], a[3]); w.z = pk2(b[0], b[1]); w.w = pk2(b[2], b[3]); return w; }
; DI float sigmoidf_(float v) { return __fdividef(1.f, 1.f + __expf(-v)); }
; template <int PH>
; DI void epilogue(const Params& p, const f32x4 (&acc)[2][2][4][2], const Unit& u, int wr, int wc, int fr, int fq) {
;     ...
;                         } else if (kind == K_GATE) {
; #pragma unroll
;                             for (int j = 0; j < 4; ++j) { v0[j] = sigmoidf_(v0[j]); v1[j] = sigmoidf_(v1[j]); }
;                         } else { v0 = v0 * sc; v1 = v1 * sc; }
;                         *(u32x4*)(d + 32 * bj) = pack8(v0, v1);
.LBB0_399:
	s_andn2_b64 vcc, exec, s[70:71]
	s_cbranch_vccnz .LBB0_401
	v_mul_f32_e32 v130, 0xbfb8aa3b, v113
	v_mul_f32_e32 v131, 0xbfb8aa3b, v114
	v_exp_f32_e32 v133, v130
	v_mul_f32_e32 v130, 0xbfb8aa3b, v118
	v_exp_f32_e32 v134, v131
	v_mul_f32_e32 v131, 0xbfb8aa3b, v119
	v_exp_f32_e32 v130, v130
	v_exp_f32_e32 v131, v131
	v_mul_f32_e32 v129, 0xbfb8aa3b, v112
	v_mul_f32_e32 v128, 0xbfb8aa3b, v116
	v_exp_f32_e32 v132, v129
	v_pk_add_f32 v[130:131], v[130:131], 1.0 op_sel_hi:[1,0]
	v_mul_f32_e32 v129, 0xbfb8aa3b, v117
	v_exp_f32_e32 v128, v128
	v_exp_f32_e32 v129, v129
	v_pk_add_f32 v[132:133], v[132:133], 1.0 op_sel_hi:[1,0]
	v_rcp_f32_e32 v131, v131
	v_pk_add_f32 v[128:129], v[128:129], 1.0 op_sel_hi:[1,0]
	v_rcp_f32_e32 v130, v130
	s_nop 0
	v_rcp_f32_e32 v129, v129
	s_nop 0
	v_rcp_f32_e32 v128, v128
	v_mul_f32_e32 v135, 0xbfb8aa3b, v115
	v_exp_f32_e32 v135, v135
	s_nop 0
	v_pk_add_f32 v[134:135], v[134:135], 1.0 op_sel_hi:[1,0]
	s_nop 0
	s_nop 0
	v_rcp_f32_e32 v135, v135
	s_nop 0
	v_rcp_f32_e32 v134, v134
	s_nop 0
	v_rcp_f32_e32 v133, v133
	s_nop 0
	v_rcp_f32_e32 v132, v132

; DI float sigmoidf_(float v) { return __fdividef(1.f, 1.f + __expf(-v)); }
; template <int PH>
; DI void epilogue(const Params& p, const f32x4 (&acc)[2][2][4][2], const Unit& u, int wr, int wc, int fr, int fq) {
;     ...
;                         if (kind == K_SILU) {
; #pragma unroll
;                             for (int j = 0; j < 4; ++j) { v0[j] = v0[j] * sigmoidf_(v0[j]); v1[j] = v1[j] * sigmoidf_(v1[j]); }
.LBB0_402:
	s_andn2_b64 vcc, exec, s[70:71]
	s_cbranch_vccnz .LBB0_404
	v_mul_f32_e32 v129, 0xbfb8aa3b, v112
	v_mul_f32_e32 v128, 0xbfb8aa3b, v116
	v_exp_f32_e32 v132, v129
	v_mul_f32_e32 v129, 0xbfb8aa3b, v117
	v_exp_f32_e32 v128, v128
	v_exp_f32_e32 v129, v129
	v_mul_f32_e32 v130, 0xbfb8aa3b, v113
	v_mul_f32_e32 v131, 0xbfb8aa3b, v114
	v_exp_f32_e32 v133, v130
	v_pk_add_f32 v[128:129], v[128:129], 1.0 op_sel_hi:[1,0]
	v_mul_f32_e32 v130, 0xbfb8aa3b, v118
	v_exp_f32_e32 v134, v131
	v_mul_f32_e32 v131, 0xbfb8aa3b, v119
	v_exp_f32_e32 v130, v130
	v_rcp_f32_e32 v129, v129
	v_exp_f32_e32 v131, v131
	v_pk_add_f32 v[132:133], v[132:133], 1.0 op_sel_hi:[1,0]
	v_pk_add_f32 v[130:131], v[130:131], 1.0 op_sel_hi:[1,0]
	v_rcp_f32_e32 v128, v128
	s_nop 0
	v_pk_mul_f32 v[128:129], v[116:117], v[128:129]
	v_rcp_f32_e32 v131, v131
	s_nop 0
	v_rcp_f32_e32 v130, v130
	v_mul_f32_e32 v135, 0xbfb8aa3b, v115
	v_exp_f32_e32 v135, v135
	v_rcp_f32_e32 v133, v133
	v_pk_add_f32 v[134:135], v[134:135], 1.0 op_sel_hi:[1,0]
	v_pk_mul_f32 v[130:131], v[118:119], v[130:131]
	v_rcp_f32_e32 v132, v132
	s_nop 0
	v_pk_mul_f32 v[132:133], v[112:113], v[132:133]
	v_rcp_f32_e32 v135, v135
	s_nop 0
	v_rcp_f32_e32 v134, v134
	s_nop 0
	v_pk_mul_f32 v[134:135], v[114:115], v[134:135]

; DI u32x4 pack8(f32x4 a, f32x4 b) { u32x4 w; w.x = pk2(a[0], a[1]); w.y = pk2(a[2], a[3]); w.z = pk2(b[0], b[1]); w.w = pk2(b[2], b[3]); return w; }
; DI float sigmoidf_(float v) { return __fdividef(1.f, 1.f + __expf(-v)); }
; template <int PH>
; DI void epilogue(const Params& p, const f32x4 (&acc)[2][2][4][2], const Unit& u, int wr, int wc, int fr, int fq) {
;     ...
;                         } else if (kind == K_GATE) {
; #pragma unroll
;                             for (int j = 0; j < 4; ++j) { v0[j] = sigmoidf_(v0[j]); v1[j] = sigmoidf_(v1[j]); }
;                         } else { v0 = v0 * sc; v1 = v1 * sc; }
;                         *(u32x4*)(d + 32 * bj) = pack8(v0, v1);
.LBB0_407:
	s_andn2_b64 vcc, exec, s[70:71]
	s_cbranch_vccnz .LBB0_409
	v_mul_f32_e32 v130, 0xbfb8aa3b, v81
	v_mul_f32_e32 v131, 0xbfb8aa3b, v82
	v_exp_f32_e32 v133, v130
	v_mul_f32_e32 v130, 0xbfb8aa3b, v86
	v_exp_f32_e32 v134, v131
	v_mul_f32_e32 v131, 0xbfb8aa3b, v87
	v_exp_f32_e32 v130, v130
	v_exp_f32_e32 v131, v131
	v_mul_f32_e32 v129, 0xbfb8aa3b, v80
	v_mul_f32_e32 v128, 0xbfb8aa3b, v84
	v_exp_f32_e32 v132, v129
	v_pk_add_f32 v[130:131], v[130:131], 1.0 op_sel_hi:[1,0]
	v_mul_f32_e32 v129, 0xbfb8aa3b, v85
	v_exp_f32_e32 v128, v128
	v_exp_f32_e32 v129, v129
	v_pk_add_f32 v[132:133], v[132:133], 1.0 op_sel_hi:[1,0]
	v_rcp_f32_e32 v131, v131
	v_pk_add_f32 v[128:129], v[128:129], 1.0 op_sel_hi:[1,0]
	v_rcp_f32_e32 v130, v130
	s_nop 0
	v_rcp_f32_e32 v129, v129
	s_nop 0
	v_rcp_f32_e32 v128, v128
	v_mul_f32_e32 v135, 0xbfb8aa3b, v83
	v_exp_f32_e32 v135, v135
	s_nop 0
	v_pk_add_f32 v[134:135], v[134:135], 1.0 op_sel_hi:[1,0]
	s_nop 0
	s_nop 0
	v_rcp_f32_e32 v135, v135
	s_nop 0
	v_rcp_f32_e32 v134, v134
	s_nop 0
	v_rcp_f32_e32 v133, v133
	s_nop 0
	v_rcp_f32_e32 v132, v132

; DI float sigmoidf_(float v) { return __fdividef(1.f, 1.f + __expf(-v)); }
; template <int PH>
; DI void epilogue(const Params& p, const f32x4 (&acc)[2][2][4][2], const Unit& u, int wr, int wc, int fr, int fq) {
;     ...
;                         if (kind == K_SILU) {
; #pragma unroll
;                             for (int j = 0; j < 4; ++j) { v0[j] = v0[j] * sigmoidf_(v0[j]); v1[j] = v1[j] * sigmoidf_(v1[j]); }
.LBB0_410:
	s_andn2_b64 vcc, exec, s[70:71]
	s_cbranch_vccnz .LBB0_412
	v_mul_f32_e32 v129, 0xbfb8aa3b, v80
	v_mul_f32_e32 v128, 0xbfb8aa3b, v84
	v_exp_f32_e32 v132, v129
	v_mul_f32_e32 v129, 0xbfb8aa3b, v85
	v_exp_f32_e32 v128, v128
	v_exp_f32_e32 v129, v129
	v_mul_f32_e32 v130, 0xbfb8aa3b, v81
	v_mul_f32_e32 v131, 0xbfb8aa3b, v82
	v_exp_f32_e32 v133, v130
	v_pk_add_f32 v[128:129], v[128:129], 1.0 op_sel_hi:[1,0]
	v_mul_f32_e32 v130, 0xbfb8aa3b, v86
	v_exp_f32_e32 v134, v131
	v_mul_f32_e32 v131, 0xbfb8aa3b, v87
	v_exp_f32_e32 v130, v130
	v_rcp_f32_e32 v129, v129
	v_exp_f32_e32 v131, v131
	v_pk_add_f32 v[132:133], v[132:133], 1.0 op_sel_hi:[1,0]
	v_pk_add_f32 v[130:131], v[130:131], 1.0 op_sel_hi:[1,0]
	v_rcp_f32_e32 v128, v128
	s_nop 0
	v_pk_mul_f32 v[128:129], v[84:85], v[128:129]
	v_rcp_f32_e32 v131, v131
	s_nop 0
	v_rcp_f32_e32 v130, v130
	v_mul_f32_e32 v135, 0xbfb8aa3b, v83
	v_exp_f32_e32 v135, v135
	v_rcp_f32_e32 v133, v133
	v_pk_add_f32 v[134:135], v[134:135], 1.0 op_sel_hi:[1,0]
	v_pk_mul_f32 v[130:131], v[86:87], v[130:131]
	v_rcp_f32_e32 v132, v132
	s_nop 0
	v_pk_mul_f32 v[132:133], v[80:81], v[132:133]
	v_rcp_f32_e32 v135, v135
	s_nop 0
	v_rcp_f32_e32 v134, v134
	s_nop 0
	v_pk_mul_f32 v[134:135], v[82:83], v[134:135]

; DI u32x4 pack8(f32x4 a, f32x4 b) { u32x4 w; w.x = pk2(a[0], a[1]); w.y = pk2(a[2], a[3]); w.z = pk2(b[0], b[1]); w.w = pk2(b[2], b[3]); return w; }
; DI float sigmoidf_(float v) { return __fdividef(1.f, 1.f + __expf(-v)); }
; template <int PH>
; DI void epilogue(const Params& p, const f32x4 (&acc)[2][2][4][2], const Unit& u, int wr, int wc, int fr, int fq) {
;     ...
;                         } else if (kind == K_GATE) {
; #pragma unroll
;                             for (int j = 0; j < 4; ++j) { v0[j] = sigmoidf_(v0[j]); v1[j] = sigmoidf_(v1[j]); }
;                         } else { v0 = v0 * sc; v1 = v1 * sc; }
;                         *(u32x4*)(d + 32 * bj) = pack8(v0, v1);
.LBB0_415:
	s_andn2_b64 vcc, exec, s[70:71]
	s_cbranch_vccnz .LBB0_417
	v_mul_f32_e32 v130, 0xbfb8aa3b, v105
	v_mul_f32_e32 v131, 0xbfb8aa3b, v106
	v_exp_f32_e32 v133, v130
	v_mul_f32_e32 v130, 0xbfb8aa3b, v110
	v_exp_f32_e32 v134, v131
	v_mul_f32_e32 v131, 0xbfb8aa3b, v111
	v_exp_f32_e32 v130, v130
	v_exp_f32_e32 v131, v131
	v_mul_f32_e32 v129, 0xbfb8aa3b, v104
	v_mul_f32_e32 v128, 0xbfb8aa3b, v108
	v_exp_f32_e32 v132, v129
	v_pk_add_f32 v[130:131], v[130:131], 1.0 op_sel_hi:[1,0]
	v_mul_f32_e32 v129, 0xbfb8aa3b, v109
	v_exp_f32_e32 v128, v128
	v_exp_f32_e32 v129, v129
	v_pk_add_f32 v[132:133], v[132:133], 1.0 op_sel_hi:[1,0]
	v_rcp_f32_e32 v131, v131
	v_pk_add_f32 v[128:129], v[128:129], 1.0 op_sel_hi:[1,0]
	v_rcp_f32_e32 v130, v130
	s_nop 0
	v_rcp_f32_e32 v129, v129
	s_nop 0
	v_rcp_f32_e32 v128, v128
	v_mul_f32_e32 v135, 0xbfb8aa3b, v107
	v_exp_f32_e32 v135, v135
	s_nop 0
	v_pk_add_f32 v[134:135], v[134:135], 1.0 op_sel_hi:[1,0]
	s_nop 0
	s_nop 0
	v_rcp_f32_e32 v135, v135
	s_nop 0
	v_rcp_f32_e32 v134, v134
	s_nop 0
	v_rcp_f32_e32 v133, v133
	s_nop 0
	v_rcp_f32_e32 v132, v132

; DI float sigmoidf_(float v) { return __fdividef(1.f, 1.f + __expf(-v)); }
; template <int PH>
; DI void epilogue(const Params& p, const f32x4 (&acc)[2][2][4][2], const Unit& u, int wr, int wc, int fr, int fq) {
;     ...
;                         if (kind == K_SILU) {
; #pragma unroll
;                             for (int j = 0; j < 4; ++j) { v0[j] = v0[j] * sigmoidf_(v0[j]); v1[j] = v1[j] * sigmoidf_(v1[j]); }
.LBB0_418:
	s_andn2_b64 vcc, exec, s[70:71]
	s_cbranch_vccnz .LBB0_420
	v_mul_f32_e32 v129, 0xbfb8aa3b, v104
	v_mul_f32_e32 v128, 0xbfb8aa3b, v108
	v_exp_f32_e32 v132, v129
	v_mul_f32_e32 v129, 0xbfb8aa3b, v109
	v_exp_f32_e32 v128, v128
	v_exp_f32_e32 v129, v129
	v_mul_f32_e32 v130, 0xbfb8aa3b, v105
	v_mul_f32_e32 v131, 0xbfb8aa3b, v106
	v_exp_f32_e32 v133, v130
	v_pk_add_f32 v[128:129], v[128:129], 1.0 op_sel_hi:[1,0]
	v_mul_f32_e32 v130, 0xbfb8aa3b, v110
	v_exp_f32_e32 v134, v131
	v_mul_f32_e32 v131, 0xbfb8aa3b, v111
	v_exp_f32_e32 v130, v130
	v_rcp_f32_e32 v129, v129
	v_exp_f32_e32 v131, v131
	v_pk_add_f32 v[132:133], v[132:133], 1.0 op_sel_hi:[1,0]
	v_pk_add_f32 v[130:131], v[130:131], 1.0 op_sel_hi:[1,0]
	v_rcp_f32_e32 v128, v128
	s_nop 0
	v_pk_mul_f32 v[128:129], v[108:109], v[128:129]
	v_rcp_f32_e32 v131, v131
	s_nop 0
	v_rcp_f32_e32 v130, v130
	v_mul_f32_e32 v135, 0xbfb8aa3b, v107
	v_exp_f32_e32 v135, v135
	v_rcp_f32_e32 v133, v133
	v_pk_add_f32 v[134:135], v[134:135], 1.0 op_sel_hi:[1,0]
	v_pk_mul_f32 v[130:131], v[110:111], v[130:131]
	v_rcp_f32_e32 v132, v132
	s_nop 0
	v_pk_mul_f32 v[132:133], v[104:105], v[132:133]
	v_rcp_f32_e32 v135, v135
	s_nop 0
	v_rcp_f32_e32 v134, v134
	s_nop 0
	v_pk_mul_f32 v[134:135], v[106:107], v[134:135]

; DI u32x4 pack8(f32x4 a, f32x4 b) { u32x4 w; w.x = pk2(a[0], a[1]); w.y = pk2(a[2], a[3]); w.z = pk2(b[0], b[1]); w.w = pk2(b[2], b[3]); return w; }
; DI float sigmoidf_(float v) { return __fdividef(1.f, 1.f + __expf(-v)); }
; template <int PH>
; DI void epilogue(const Params& p, const f32x4 (&acc)[2][2][4][2], const Unit& u, int wr, int wc, int fr, int fq) {
;     ...
;                         } else if (kind == K_GATE) {
; #pragma unroll
;                             for (int j = 0; j < 4; ++j) { v0[j] = sigmoidf_(v0[j]); v1[j] = sigmoidf_(v1[j]); }
;                         } else { v0 = v0 * sc; v1 = v1 * sc; }
;                         *(u32x4*)(d + 32 * bj) = pack8(v0, v1);
.LBB0_423:
	s_andn2_b64 vcc, exec, s[70:71]
	s_cbranch_vccnz .LBB0_425
	v_mul_f32_e32 v130, 0xbfb8aa3b, v73
	v_mul_f32_e32 v131, 0xbfb8aa3b, v74
	v_exp_f32_e32 v133, v130
	v_mul_f32_e32 v130, 0xbfb8aa3b, v78
	v_exp_f32_e32 v134, v131
	v_mul_f32_e32 v131, 0xbfb8aa3b, v79
	v_exp_f32_e32 v130, v130
	v_exp_f32_e32 v131, v131
	v_mul_f32_e32 v129, 0xbfb8aa3b, v72
	v_mul_f32_e32 v128, 0xbfb8aa3b, v76
	v_exp_f32_e32 v132, v129
	v_pk_add_f32 v[130:131], v[130:131], 1.0 op_sel_hi:[1,0]
	v_mul_f32_e32 v129, 0xbfb8aa3b, v77
	v_exp_f32_e32 v128, v128
	v_exp_f32_e32 v129, v129
	v_pk_add_f32 v[132:133], v[132:133], 1.0 op_sel_hi:[1,0]
	v_rcp_f32_e32 v131, v131
	v_pk_add_f32 v[128:129], v[128:129], 1.0 op_sel_hi:[1,0]
	v_rcp_f32_e32 v130, v130
	s_nop 0
	v_rcp_f32_e32 v129, v129
	s_nop 0
	v_rcp_f32_e32 v128, v128
	v_mul_f32_e32 v135, 0xbfb8aa3b, v75
	v_exp_f32_e32 v135, v135
	s_nop 0
	v_pk_add_f32 v[134:135], v[134:135], 1.0 op_sel_hi:[1,0]
	s_nop 0
	s_nop 0
	v_rcp_f32_e32 v135, v135
	s_nop 0
	v_rcp_f32_e32 v134, v134
	s_nop 0
	v_rcp_f32_e32 v133, v133
	s_nop 0
	v_rcp_f32_e32 v132, v132

; DI float sigmoidf_(float v) { return __fdividef(1.f, 1.f + __expf(-v)); }
; template <int PH>
; DI void epilogue(const Params& p, const f32x4 (&acc)[2][2][4][2], const Unit& u, int wr, int wc, int fr, int fq) {
;     ...
;                         if (kind == K_SILU) {
; #pragma unroll
;                             for (int j = 0; j < 4; ++j) { v0[j] = v0[j] * sigmoidf_(v0[j]); v1[j] = v1[j] * sigmoidf_(v1[j]); }
.LBB0_426:
	s_andn2_b64 vcc, exec, s[70:71]
	s_cbranch_vccnz .LBB0_428
	v_mul_f32_e32 v129, 0xbfb8aa3b, v72
	v_mul_f32_e32 v128, 0xbfb8aa3b, v76
	v_exp_f32_e32 v132, v129
	v_mul_f32_e32 v129, 0xbfb8aa3b, v77
	v_exp_f32_e32 v128, v128
	v_exp_f32_e32 v129, v129
	v_mul_f32_e32 v130, 0xbfb8aa3b, v73
	v_mul_f32_e32 v131, 0xbfb8aa3b, v74
	v_exp_f32_e32 v133, v130
	v_pk_add_f32 v[128:129], v[128:129], 1.0 op_sel_hi:[1,0]
	v_mul_f32_e32 v130, 0xbfb8aa3b, v78
	v_exp_f32_e32 v134, v131
	v_mul_f32_e32 v131, 0xbfb8aa3b, v79
	v_exp_f32_e32 v130, v130
	v_rcp_f32_e32 v129, v129
	v_exp_f32_e32 v131, v131
	v_pk_add_f32 v[132:133], v[132:133], 1.0 op_sel_hi:[1,0]
	v_pk_add_f32 v[130:131], v[130:131], 1.0 op_sel_hi:[1,0]
	v_rcp_f32_e32 v128, v128
	s_nop 0
	v_pk_mul_f32 v[128:129], v[76:77], v[128:129]
	v_rcp_f32_e32 v131, v131
	s_nop 0
	v_rcp_f32_e32 v130, v130
	v_mul_f32_e32 v135, 0xbfb8aa3b, v75
	v_exp_f32_e32 v135, v135
	v_rcp_f32_e32 v133, v133
	v_pk_add_f32 v[134:135], v[134:135], 1.0 op_sel_hi:[1,0]
	v_pk_mul_f32 v[130:131], v[78:79], v[130:131]
	v_rcp_f32_e32 v132, v132
	s_nop 0
	v_pk_mul_f32 v[132:133], v[72:73], v[132:133]
	v_rcp_f32_e32 v135, v135
	s_nop 0
	v_rcp_f32_e32 v134, v134
	s_nop 0
	v_pk_mul_f32 v[134:135], v[74:75], v[134:135]

; DI u32x4 pack8(f32x4 a, f32x4 b) { u32x4 w; w.x = pk2(a[0], a[1]); w.y = pk2(a[2], a[3]); w.z = pk2(b[0], b[1]); w.w = pk2(b[2], b[3]); return w; }
; DI float sigmoidf_(float v) { return __fdividef(1.f, 1.f + __expf(-v)); }
; template <int PH>
; DI void epilogue(const Params& p, const f32x4 (&acc)[2][2][4][2], const Unit& u, int wr, int wc, int fr, int fq) {
;     ...
;                         } else if (kind == K_GATE) {
; #pragma unroll
;                             for (int j = 0; j < 4; ++j) { v0[j] = sigmoidf_(v0[j]); v1[j] = sigmoidf_(v1[j]); }
;                         } else { v0 = v0 * sc; v1 = v1 * sc; }
;                         *(u32x4*)(d + 32 * bj) = pack8(v0, v1);
.LBB0_431:
	s_andn2_b64 vcc, exec, s[70:71]
	s_cbranch_vccnz .LBB0_433
	v_mul_f32_e32 v130, 0xbfb8aa3b, v97
	v_mul_f32_e32 v131, 0xbfb8aa3b, v98
	v_exp_f32_e32 v133, v130
	v_mul_f32_e32 v130, 0xbfb8aa3b, v102
	v_exp_f32_e32 v134, v131
	v_mul_f32_e32 v131, 0xbfb8aa3b, v103
	v_exp_f32_e32 v130, v130
	v_exp_f32_e32 v131, v131
	v_mul_f32_e32 v129, 0xbfb8aa3b, v96
	v_mul_f32_e32 v128, 0xbfb8aa3b, v100
	v_exp_f32_e32 v132, v129
	v_pk_add_f32 v[130:131], v[130:131], 1.0 op_sel_hi:[1,0]
	v_mul_f32_e32 v129, 0xbfb8aa3b, v101
	v_exp_f32_e32 v128, v128
	v_exp_f32_e32 v129, v129
	v_pk_add_f32 v[132:133], v[132:133], 1.0 op_sel_hi:[1,0]
	v_rcp_f32_e32 v131, v131
	v_pk_add_f32 v[128:129], v[128:129], 1.0 op_sel_hi:[1,0]
	v_rcp_f32_e32 v130, v130
	s_nop 0
	v_rcp_f32_e32 v129, v129
	s_nop 0
	v_rcp_f32_e32 v128, v128
	v_mul_f32_e32 v135, 0xbfb8aa3b, v99
	v_exp_f32_e32 v135, v135
	s_nop 0
	v_pk_add_f32 v[134:135], v[134:135], 1.0 op_sel_hi:[1,0]
	s_nop 0
	s_nop 0
	v_rcp_f32_e32 v135, v135
	s_nop 0
	v_rcp_f32_e32 v134, v134
	s_nop 0
	v_rcp_f32_e32 v133, v133
	s_nop 0
	v_rcp_f32_e32 v132, v132

; DI float sigmoidf_(float v) { return __fdividef(1.f, 1.f + __expf(-v)); }
; template <int PH>
; DI void epilogue(const Params& p, const f32x4 (&acc)[2][2][4][2], const Unit& u, int wr, int wc, int fr, int fq) {
;     ...
;                         if (kind == K_SILU) {
; #pragma unroll
;                             for (int j = 0; j < 4; ++j) { v0[j] = v0[j] * sigmoidf_(v0[j]); v1[j] = v1[j] * sigmoidf_(v1[j]); }
.LBB0_434:
	s_andn2_b64 vcc, exec, s[70:71]
	s_cbranch_vccnz .LBB0_436
	v_mul_f32_e32 v129, 0xbfb8aa3b, v96
	v_mul_f32_e32 v128, 0xbfb8aa3b, v100
	v_exp_f32_e32 v132, v129
	v_mul_f32_e32 v129, 0xbfb8aa3b, v101
	v_exp_f32_e32 v128, v128
	v_exp_f32_e32 v129, v129
	v_mul_f32_e32 v130, 0xbfb8aa3b, v97
	v_mul_f32_e32 v131, 0xbfb8aa3b, v98
	v_exp_f32_e32 v133, v130
	v_pk_add_f32 v[128:129], v[128:129], 1.0 op_sel_hi:[1,0]
	v_mul_f32_e32 v130, 0xbfb8aa3b, v102
	v_exp_f32_e32 v134, v131
	v_mul_f32_e32 v131, 0xbfb8aa3b, v103
	v_exp_f32_e32 v130, v130
	v_rcp_f32_e32 v129, v129
	v_exp_f32_e32 v131, v131
	v_pk_add_f32 v[132:133], v[132:133], 1.0 op_sel_hi:[1,0]
	v_pk_add_f32 v[130:131], v[130:131], 1.0 op_sel_hi:[1,0]
	v_rcp_f32_e32 v128, v128
	s_nop 0
	v_pk_mul_f32 v[128:129], v[100:101], v[128:129]
	v_rcp_f32_e32 v131, v131
	s_nop 0
	v_rcp_f32_e32 v130, v130
	v_mul_f32_e32 v135, 0xbfb8aa3b, v99
	v_exp_f32_e32 v135, v135
	v_rcp_f32_e32 v133, v133
	v_pk_add_f32 v[134:135], v[134:135], 1.0 op_sel_hi:[1,0]
	v_pk_mul_f32 v[130:131], v[102:103], v[130:131]
	v_rcp_f32_e32 v132, v132
	s_nop 0
	v_pk_mul_f32 v[132:133], v[96:97], v[132:133]
	v_rcp_f32_e32 v135, v135
	s_nop 0
	v_rcp_f32_e32 v134, v134
	s_nop 0
	v_pk_mul_f32 v[134:135], v[98:99], v[134:135]

; DI u32x4 pack8(f32x4 a, f32x4 b) { u32x4 w; w.x = pk2(a[0], a[1]); w.y = pk2(a[2], a[3]); w.z = pk2(b[0], b[1]); w.w = pk2(b[2], b[3]); return w; }
; DI float sigmoidf_(float v) { return __fdividef(1.f, 1.f + __expf(-v)); }
; template <int PH>
; DI void epilogue(const Params& p, const f32x4 (&acc)[2][2][4][2], const Unit& u, int wr, int wc, int fr, int fq) {
;     ...
;                         } else if (kind == K_GATE) {
; #pragma unroll
;                             for (int j = 0; j < 4; ++j) { v0[j] = sigmoidf_(v0[j]); v1[j] = sigmoidf_(v1[j]); }
;                         } else { v0 = v0 * sc; v1 = v1 * sc; }
;                         *(u32x4*)(d + 32 * bj) = pack8(v0, v1);
.LBB0_439:
	s_andn2_b64 vcc, exec, s[70:71]
	s_cbranch_vccnz .LBB0_441
	v_mul_f32_e32 v130, 0xbfb8aa3b, v65
	v_mul_f32_e32 v131, 0xbfb8aa3b, v66
	v_exp_f32_e32 v133, v130
	v_mul_f32_e32 v130, 0xbfb8aa3b, v70
	v_exp_f32_e32 v134, v131
	v_mul_f32_e32 v131, 0xbfb8aa3b, v71
	v_exp_f32_e32 v130, v130
	v_exp_f32_e32 v131, v131
	v_mul_f32_e32 v129, 0xbfb8aa3b, v64
	v_mul_f32_e32 v128, 0xbfb8aa3b, v68
	v_exp_f32_e32 v132, v129
	v_pk_add_f32 v[130:131], v[130:131], 1.0 op_sel_hi:[1,0]
	v_mul_f32_e32 v129, 0xbfb8aa3b, v69
	v_exp_f32_e32 v128, v128
	v_exp_f32_e32 v129, v129
	v_pk_add_f32 v[132:133], v[132:133], 1.0 op_sel_hi:[1,0]
	v_rcp_f32_e32 v131, v131
	v_pk_add_f32 v[128:129], v[128:129], 1.0 op_sel_hi:[1,0]
	v_rcp_f32_e32 v130, v130
	s_nop 0
	v_rcp_f32_e32 v129, v129
	s_nop 0
	v_rcp_f32_e32 v128, v128
	v_mul_f32_e32 v135, 0xbfb8aa3b, v67
	v_exp_f32_e32 v135, v135
	s_nop 0
	v_pk_add_f32 v[134:135], v[134:135], 1.0 op_sel_hi:[1,0]
	s_nop 0
	s_nop 0
	v_rcp_f32_e32 v135, v135
	s_nop 0
	v_rcp_f32_e32 v134, v134
	s_nop 0
	v_rcp_f32_e32 v133, v133
	s_nop 0
	v_rcp_f32_e32 v132, v132

; DI float sigmoidf_(float v) { return __fdividef(1.f, 1.f + __expf(-v)); }
; template <int PH>
; DI void epilogue(const Params& p, const f32x4 (&acc)[2][2][4][2], const Unit& u, int wr, int wc, int fr, int fq) {
;     ...
;                         if (kind == K_SILU) {
; #pragma unroll
;                             for (int j = 0; j < 4; ++j) { v0[j] = v0[j] * sigmoidf_(v0[j]); v1[j] = v1[j] * sigmoidf_(v1[j]); }
.LBB0_442:
	s_andn2_b64 vcc, exec, s[70:71]
	s_cbranch_vccnz .LBB0_444
	v_mul_f32_e32 v129, 0xbfb8aa3b, v64
	v_mul_f32_e32 v128, 0xbfb8aa3b, v68
	v_exp_f32_e32 v132, v129
	v_mul_f32_e32 v129, 0xbfb8aa3b, v69
	v_exp_f32_e32 v128, v128
	v_exp_f32_e32 v129, v129
	v_mul_f32_e32 v130, 0xbfb8aa3b, v65
	v_mul_f32_e32 v131, 0xbfb8aa3b, v66
	v_exp_f32_e32 v133, v130
	v_pk_add_f32 v[128:129], v[128:129], 1.0 op_sel_hi:[1,0]
	v_mul_f32_e32 v130, 0xbfb8aa3b, v70
	v_exp_f32_e32 v134, v131
	v_mul_f32_e32 v131, 0xbfb8aa3b, v71
	v_exp_f32_e32 v130, v130
	v_rcp_f32_e32 v129, v129
	v_exp_f32_e32 v131, v131
	v_pk_add_f32 v[132:133], v[132:133], 1.0 op_sel_hi:[1,0]
	v_pk_add_f32 v[130:131], v[130:131], 1.0 op_sel_hi:[1,0]
	v_rcp_f32_e32 v128, v128
	s_nop 0
	v_pk_mul_f32 v[128:129], v[68:69], v[128:129]
	v_rcp_f32_e32 v131, v131
	s_nop 0
	v_rcp_f32_e32 v130, v130
	v_mul_f32_e32 v135, 0xbfb8aa3b, v67
	v_exp_f32_e32 v135, v135
	v_rcp_f32_e32 v133, v133
	v_pk_add_f32 v[134:135], v[134:135], 1.0 op_sel_hi:[1,0]
	v_pk_mul_f32 v[130:131], v[70:71], v[130:131]
	v_rcp_f32_e32 v132, v132
	s_nop 0
	v_pk_mul_f32 v[132:133], v[64:65], v[132:133]
	v_rcp_f32_e32 v135, v135
	s_nop 0
	v_rcp_f32_e32 v134, v134
	s_nop 0
	v_pk_mul_f32 v[134:135], v[66:67], v[134:135]

; DI u32x4 pack8(f32x4 a, f32x4 b) { u32x4 w; w.x = pk2(a[0], a[1]); w.y = pk2(a[2], a[3]); w.z = pk2(b[0], b[1]); w.w = pk2(b[2], b[3]); return w; }
; DI float sigmoidf_(float v) { return __fdividef(1.f, 1.f + __expf(-v)); }
; template <int PH>
; DI void epilogue(const Params& p, const f32x4 (&acc)[2][2][4][2], const Unit& u, int wr, int wc, int fr, int fq) {
;     ...
;                         } else if (kind == K_GATE) {
; #pragma unroll
;                             for (int j = 0; j < 4; ++j) { v0[j] = sigmoidf_(v0[j]); v1[j] = sigmoidf_(v1[j]); }
;                         } else { v0 = v0 * sc; v1 = v1 * sc; }
;                         *(u32x4*)(d + 32 * bj) = pack8(v0, v1);
.LBB0_447:
	s_andn2_b64 vcc, exec, s[70:71]
	s_cbranch_vccnz .LBB0_449
	v_mul_f32_e32 v130, 0xbfb8aa3b, v57
	v_mul_f32_e32 v131, 0xbfb8aa3b, v58
	v_exp_f32_e32 v133, v130
	v_mul_f32_e32 v130, 0xbfb8aa3b, v62
	v_exp_f32_e32 v134, v131
	v_mul_f32_e32 v131, 0xbfb8aa3b, v63
	v_exp_f32_e32 v130, v130
	v_exp_f32_e32 v131, v131
	v_mul_f32_e32 v129, 0xbfb8aa3b, v56
	v_mul_f32_e32 v128, 0xbfb8aa3b, v60
	v_exp_f32_e32 v132, v129
	v_pk_add_f32 v[130:131], v[130:131], 1.0 op_sel_hi:[1,0]
	v_mul_f32_e32 v129, 0xbfb8aa3b, v61
	v_exp_f32_e32 v128, v128
	v_exp_f32_e32 v129, v129
	v_pk_add_f32 v[132:133], v[132:133], 1.0 op_sel_hi:[1,0]
	v_rcp_f32_e32 v131, v131
	v_pk_add_f32 v[128:129], v[128:129], 1.0 op_sel_hi:[1,0]
	v_rcp_f32_e32 v130, v130
	s_nop 0
	v_rcp_f32_e32 v129, v129
	s_nop 0
	v_rcp_f32_e32 v128, v128
	v_mul_f32_e32 v135, 0xbfb8aa3b, v59
	v_exp_f32_e32 v135, v135
	s_nop 0
	v_pk_add_f32 v[134:135], v[134:135], 1.0 op_sel_hi:[1,0]
	s_nop 0
	s_nop 0
	v_rcp_f32_e32 v135, v135
	s_nop 0
	v_rcp_f32_e32 v134, v134
	s_nop 0
	v_rcp_f32_e32 v133, v133
	s_nop 0
	v_rcp_f32_e32 v132, v132

; DI u32x4 pack8(f32x4 a, f32x4 b) { u32x4 w; w.x = pk2(a[0], a[1]); w.y = pk2(a[2], a[3]); w.z = pk2(b[0], b[1]); w.w = pk2(b[2], b[3]); return w; }
; DI float sigmoidf_(float v) { return __fdividef(1.f, 1.f + __expf(-v)); }
; template <int PH>
; DI void epilogue(const Params& p, const f32x4 (&acc)[2][2][4][2], const Unit& u, int wr, int wc, int fr, int fq) {
;     ...
;                     for (int bj = 0; bj < 2; ++bj) {
;                         f32x4 v0 = acc[ai][bj][m][0], v1 = acc[ai][bj][m][1];
;                         if (kind == K_SILU) {
; #pragma unroll
;                             for (int j = 0; j < 4; ++j) { v0[j] = v0[j] * sigmoidf_(v0[j]); v1[j] = v1[j] * sigmoidf_(v1[j]); }
;                         } else if (kind == K_GATE) {
; #pragma unroll
;                             for (int j = 0; j < 4; ++j) { v0[j] = sigmoidf_(v0[j]); v1[j] = sigmoidf_(v1[j]); }
;                         } else { v0 = v0 * sc; v1 = v1 * sc; }
;                         *(u32x4*)(d + 32 * bj) = pack8(v0, v1);
.LBB0_450:
	s_andn2_b64 vcc, exec, s[70:71]
	s_cbranch_vccnz .LBB0_452
	v_mul_f32_e32 v129, 0xbfb8aa3b, v56
	v_mul_f32_e32 v128, 0xbfb8aa3b, v60
	v_exp_f32_e32 v132, v129
	v_mul_f32_e32 v129, 0xbfb8aa3b, v61
	v_exp_f32_e32 v128, v128
	v_exp_f32_e32 v129, v129
	v_mul_f32_e32 v130, 0xbfb8aa3b, v57
	v_mul_f32_e32 v131, 0xbfb8aa3b, v58
	v_exp_f32_e32 v133, v130
	v_pk_add_f32 v[128:129], v[128:129], 1.0 op_sel_hi:[1,0]
	v_mul_f32_e32 v130, 0xbfb8aa3b, v62
	v_exp_f32_e32 v134, v131
	v_mul_f32_e32 v131, 0xbfb8aa3b, v63
	v_exp_f32_e32 v130, v130
	v_rcp_f32_e32 v129, v129
	v_exp_f32_e32 v131, v131
	v_pk_add_f32 v[132:133], v[132:133], 1.0 op_sel_hi:[1,0]
	v_pk_add_f32 v[130:131], v[130:131], 1.0 op_sel_hi:[1,0]
	v_rcp_f32_e32 v128, v128
	s_nop 0
	v_pk_mul_f32 v[128:129], v[60:61], v[128:129]
	v_rcp_f32_e32 v131, v131
	s_nop 0
	v_rcp_f32_e32 v130, v130
	v_mul_f32_e32 v135, 0xbfb8aa3b, v59
	v_exp_f32_e32 v135, v135
	v_rcp_f32_e32 v133, v133
	v_pk_add_f32 v[134:135], v[134:135], 1.0 op_sel_hi:[1,0]
	v_pk_mul_f32 v[130:131], v[62:63], v[130:131]
	v_rcp_f32_e32 v132, v132
	s_nop 0
	v_pk_mul_f32 v[132:133], v[56:57], v[132:133]
	v_rcp_f32_e32 v135, v135
	s_nop 0
	v_rcp_f32_e32 v134, v134
	s_nop 0
	v_pk_mul_f32 v[134:135], v[58:59], v[134:135]

; DI u32x4 pack8(f32x4 a, f32x4 b) { u32x4 w; w.x = pk2(a[0], a[1]); w.y = pk2(a[2], a[3]); w.z = pk2(b[0], b[1]); w.w = pk2(b[2], b[3]); return w; }
; DI float sigmoidf_(float v) { return __fdividef(1.f, 1.f + __expf(-v)); }
; template <int PH>
; DI void epilogue(const Params& p, const f32x4 (&acc)[2][2][4][2], const Unit& u, int wr, int wc, int fr, int fq) {
;     ...
;                     for (int bj = 0; bj < 2; ++bj) {
;                         f32x4 v0 = acc[ai][bj][m][0], v1 = acc[ai][bj][m][1];
;                         if (kind == K_SILU) {
; #pragma unroll
;                             for (int j = 0; j < 4; ++j) { v0[j] = v0[j] * sigmoidf_(v0[j]); v1[j] = v1[j] * sigmoidf_(v1[j]); }
;                         } else if (kind == K_GATE) {
; #pragma unroll
;                             for (int j = 0; j < 4; ++j) { v0[j] = sigmoidf_(v0[j]); v1[j] = sigmoidf_(v1[j]); }
;                         } else { v0 = v0 * sc; v1 = v1 * sc; }
;                         *(u32x4*)(d + 32 * bj) = pack8(v0, v1);
.LBB0_455:
	s_andn2_b64 vcc, exec, s[70:71]
	s_cbranch_vccnz .LBB0_457
	v_mul_f32_e32 v130, 0xbfb8aa3b, v25
	v_mul_f32_e32 v131, 0xbfb8aa3b, v26
	v_exp_f32_e32 v133, v130
	v_mul_f32_e32 v130, 0xbfb8aa3b, v30
	v_exp_f32_e32 v134, v131
	v_mul_f32_e32 v131, 0xbfb8aa3b, v31
	v_exp_f32_e32 v130, v130
	v_exp_f32_e32 v131, v131
	v_mul_f32_e32 v129, 0xbfb8aa3b, v24
	v_mul_f32_e32 v128, 0xbfb8aa3b, v28
	v_exp_f32_e32 v132, v129
	v_pk_add_f32 v[130:131], v[130:131], 1.0 op_sel_hi:[1,0]
	v_mul_f32_e32 v129, 0xbfb8aa3b, v29
	v_exp_f32_e32 v128, v128
	v_exp_f32_e32 v129, v129
	v_pk_add_f32 v[132:133], v[132:133], 1.0 op_sel_hi:[1,0]
	v_rcp_f32_e32 v131, v131
	v_pk_add_f32 v[128:129], v[128:129], 1.0 op_sel_hi:[1,0]
	v_rcp_f32_e32 v130, v130
	s_nop 0
	v_rcp_f32_e32 v129, v129
	s_nop 0
	v_rcp_f32_e32 v128, v128
	v_mul_f32_e32 v135, 0xbfb8aa3b, v27
	v_exp_f32_e32 v135, v135
	s_nop 0
	v_pk_add_f32 v[134:135], v[134:135], 1.0 op_sel_hi:[1,0]
	s_nop 0
	s_nop 0
	v_rcp_f32_e32 v135, v135
	s_nop 0
	v_rcp_f32_e32 v134, v134
	s_nop 0
	v_rcp_f32_e32 v133, v133
	s_nop 0
	v_rcp_f32_e32 v132, v132

; DI u32x4 pack8(f32x4 a, f32x4 b) { u32x4 w; w.x = pk2(a[0], a[1]); w.y = pk2(a[2], a[3]); w.z = pk2(b[0], b[1]); w.w = pk2(b[2], b[3]); return w; }
; DI float sigmoidf_(float v) { return __fdividef(1.f, 1.f + __expf(-v)); }
; template <int PH>
; DI void epilogue(const Params& p, const f32x4 (&acc)[2][2][4][2], const Unit& u, int wr, int wc, int fr, int fq) {
;     ...
;                     for (int bj = 0; bj < 2; ++bj) {
;                         f32x4 v0 = acc[ai][bj][m][0], v1 = acc[ai][bj][m][1];
;                         if (kind == K_SILU) {
; #pragma unroll
;                             for (int j = 0; j < 4; ++j) { v0[j] = v0[j] * sigmoidf_(v0[j]); v1[j] = v1[j] * sigmoidf_(v1[j]); }
;                         } else if (kind == K_GATE) {
; #pragma unroll
;                             for (int j = 0; j < 4; ++j) { v0[j] = sigmoidf_(v0[j]); v1[j] = sigmoidf_(v1[j]); }
;                         } else { v0 = v0 * sc; v1 = v1 * sc; }
;                         *(u32x4*)(d + 32 * bj) = pack8(v0, v1);
.LBB0_458:
	s_andn2_b64 vcc, exec, s[70:71]
	s_cbranch_vccnz .LBB0_460
	v_mul_f32_e32 v129, 0xbfb8aa3b, v24
	v_mul_f32_e32 v128, 0xbfb8aa3b, v28
	v_exp_f32_e32 v132, v129
	v_mul_f32_e32 v129, 0xbfb8aa3b, v29
	v_exp_f32_e32 v128, v128
	v_exp_f32_e32 v129, v129
	v_mul_f32_e32 v130, 0xbfb8aa3b, v25
	v_mul_f32_e32 v131, 0xbfb8aa3b, v26
	v_exp_f32_e32 v133, v130
	v_pk_add_f32 v[128:129], v[128:129], 1.0 op_sel_hi:[1,0]
	v_mul_f32_e32 v130, 0xbfb8aa3b, v30
	v_exp_f32_e32 v134, v131
	v_mul_f32_e32 v131, 0xbfb8aa3b, v31
	v_exp_f32_e32 v130, v130
	v_rcp_f32_e32 v129, v129
	v_exp_f32_e32 v131, v131
	v_pk_add_f32 v[132:133], v[132:133], 1.0 op_sel_hi:[1,0]
	v_pk_add_f32 v[130:131], v[130:131], 1.0 op_sel_hi:[1,0]
	v_rcp_f32_e32 v128, v128
	s_nop 0
	v_pk_mul_f32 v[128:129], v[28:29], v[128:129]
	v_rcp_f32_e32 v131, v131
	s_nop 0
	v_rcp_f32_e32 v130, v130
	v_mul_f32_e32 v135, 0xbfb8aa3b, v27
	v_exp_f32_e32 v135, v135
	v_rcp_f32_e32 v133, v133
	v_pk_add_f32 v[134:135], v[134:135], 1.0 op_sel_hi:[1,0]
	v_pk_mul_f32 v[130:131], v[30:31], v[130:131]
	v_rcp_f32_e32 v132, v132
	s_nop 0
	v_pk_mul_f32 v[132:133], v[24:25], v[132:133]
	v_rcp_f32_e32 v135, v135
	s_nop 0
	v_rcp_f32_e32 v134, v134
	s_nop 0
	v_pk_mul_f32 v[134:135], v[26:27], v[134:135]

; DI u32x4 pack8(f32x4 a, f32x4 b) { u32x4 w; w.x = pk2(a[0], a[1]); w.y = pk2(a[2], a[3]); w.z = pk2(b[0], b[1]); w.w = pk2(b[2], b[3]); return w; }
; DI float sigmoidf_(float v) { return __fdividef(1.f, 1.f + __expf(-v)); }
; template <int PH>
; DI void epilogue(const Params& p, const f32x4 (&acc)[2][2][4][2], const Unit& u, int wr, int wc, int fr, int fq) {
;     ...
;                     for (int bj = 0; bj < 2; ++bj) {
;                         f32x4 v0 = acc[ai][bj][m][0], v1 = acc[ai][bj][m][1];
;                         if (kind == K_SILU) {
; #pragma unroll
;                             for (int j = 0; j < 4; ++j) { v0[j] = v0[j] * sigmoidf_(v0[j]); v1[j] = v1[j] * sigmoidf_(v1[j]); }
;                         } else if (kind == K_GATE) {
; #pragma unroll
;                             for (int j = 0; j < 4; ++j) { v0[j] = sigmoidf_(v0[j]); v1[j] = sigmoidf_(v1[j]); }
;                         } else { v0 = v0 * sc; v1 = v1 * sc; }
;                         *(u32x4*)(d + 32 * bj) = pack8(v0, v1);
.LBB0_463:
	s_andn2_b64 vcc, exec, s[70:71]
	s_cbranch_vccnz .LBB0_465
	v_mul_f32_e32 v130, 0xbfb8aa3b, v49
	v_mul_f32_e32 v131, 0xbfb8aa3b, v50
	v_exp_f32_e32 v133, v130
	v_mul_f32_e32 v130, 0xbfb8aa3b, v54
	v_exp_f32_e32 v134, v131
	v_mul_f32_e32 v131, 0xbfb8aa3b, v55
	v_exp_f32_e32 v130, v130
	v_exp_f32_e32 v131, v131
	v_mul_f32_e32 v129, 0xbfb8aa3b, v48
	v_mul_f32_e32 v128, 0xbfb8aa3b, v52
	v_exp_f32_e32 v132, v129
	v_pk_add_f32 v[130:131], v[130:131], 1.0 op_sel_hi:[1,0]
	v_mul_f32_e32 v129, 0xbfb8aa3b, v53
	v_exp_f32_e32 v128, v128
	v_exp_f32_e32 v129, v129
	v_pk_add_f32 v[132:133], v[132:133], 1.0 op_sel_hi:[1,0]
	v_rcp_f32_e32 v131, v131
	v_pk_add_f32 v[128:129], v[128:129], 1.0 op_sel_hi:[1,0]
	v_rcp_f32_e32 v130, v130
	s_nop 0
	v_rcp_f32_e32 v129, v129
	s_nop 0
	v_rcp_f32_e32 v128, v128
	v_mul_f32_e32 v135, 0xbfb8aa3b, v51
	v_exp_f32_e32 v135, v135
	s_nop 0
	v_pk_add_f32 v[134:135], v[134:135], 1.0 op_sel_hi:[1,0]
	s_nop 0
	s_nop 0
	v_rcp_f32_e32 v135, v135
	s_nop 0
	v_rcp_f32_e32 v134, v134
	s_nop 0
	v_rcp_f32_e32 v133, v133
	s_nop 0
	v_rcp_f32_e32 v132, v132

; DI u32x4 pack8(f32x4 a, f32x4 b) { u32x4 w; w.x = pk2(a[0], a[1]); w.y = pk2(a[2], a[3]); w.z = pk2(b[0], b[1]); w.w = pk2(b[2], b[3]); return w; }
; DI float sigmoidf_(float v) { return __fdividef(1.f, 1.f + __expf(-v)); }
; template <int PH>
; DI void epilogue(const Params& p, const f32x4 (&acc)[2][2][4][2], const Unit& u, int wr, int wc, int fr, int fq) {
;     ...
;                     for (int bj = 0; bj < 2; ++bj) {
;                         f32x4 v0 = acc[ai][bj][m][0], v1 = acc[ai][bj][m][1];
;                         if (kind == K_SILU) {
; #pragma unroll
;                             for (int j = 0; j < 4; ++j) { v0[j] = v0[j] * sigmoidf_(v0[j]); v1[j] = v1[j] * sigmoidf_(v1[j]); }
;                         } else if (kind == K_GATE) {
; #pragma unroll
;                             for (int j = 0; j < 4; ++j) { v0[j] = sigmoidf_(v0[j]); v1[j] = sigmoidf_(v1[j]); }
;                         } else { v0 = v0 * sc; v1 = v1 * sc; }
;                         *(u32x4*)(d + 32 * bj) = pack8(v0, v1);
.LBB0_466:
	s_andn2_b64 vcc, exec, s[70:71]
	s_cbranch_vccnz .LBB0_468
	v_mul_f32_e32 v129, 0xbfb8aa3b, v48
	v_mul_f32_e32 v128, 0xbfb8aa3b, v52
	v_exp_f32_e32 v132, v129
	v_mul_f32_e32 v129, 0xbfb8aa3b, v53
	v_exp_f32_e32 v128, v128
	v_exp_f32_e32 v129, v129
	v_mul_f32_e32 v130, 0xbfb8aa3b, v49
	v_mul_f32_e32 v131, 0xbfb8aa3b, v50
	v_exp_f32_e32 v133, v130
	v_pk_add_f32 v[128:129], v[128:129], 1.0 op_sel_hi:[1,0]
	v_mul_f32_e32 v130, 0xbfb8aa3b, v54
	v_exp_f32_e32 v134, v131
	v_mul_f32_e32 v131, 0xbfb8aa3b, v55
	v_exp_f32_e32 v130, v130
	v_rcp_f32_e32 v129, v129
	v_exp_f32_e32 v131, v131
	v_pk_add_f32 v[132:133], v[132:133], 1.0 op_sel_hi:[1,0]
	v_pk_add_f32 v[130:131], v[130:131], 1.0 op_sel_hi:[1,0]
	v_rcp_f32_e32 v128, v128
	s_nop 0
	v_pk_mul_f32 v[128:129], v[52:53], v[128:129]
	v_rcp_f32_e32 v131, v131
	s_nop 0
	v_rcp_f32_e32 v130, v130
	v_mul_f32_e32 v135, 0xbfb8aa3b, v51
	v_exp_f32_e32 v135, v135
	v_rcp_f32_e32 v133, v133
	v_pk_add_f32 v[134:135], v[134:135], 1.0 op_sel_hi:[1,0]
	v_pk_mul_f32 v[130:131], v[54:55], v[130:131]
	v_rcp_f32_e32 v132, v132
	s_nop 0
	v_pk_mul_f32 v[132:133], v[48:49], v[132:133]
	v_rcp_f32_e32 v135, v135
	s_nop 0
	v_rcp_f32_e32 v134, v134
	s_nop 0
	v_pk_mul_f32 v[134:135], v[50:51], v[134:135]

; DI u32x4 pack8(f32x4 a, f32x4 b) { u32x4 w; w.x = pk2(a[0], a[1]); w.y = pk2(a[2], a[3]); w.z = pk2(b[0], b[1]); w.w = pk2(b[2], b[3]); return w; }
; DI float sigmoidf_(float v) { return __fdividef(1.f, 1.f + __expf(-v)); }
; template <int PH>
; DI void epilogue(const Params& p, const f32x4 (&acc)[2][2][4][2], const Unit& u, int wr, int wc, int fr, int fq) {
;     ...
;                     for (int bj = 0; bj < 2; ++bj) {
;                         f32x4 v0 = acc[ai][bj][m][0], v1 = acc[ai][bj][m][1];
;                         if (kind == K_SILU) {
; #pragma unroll
;                             for (int j = 0; j < 4; ++j) { v0[j] = v0[j] * sigmoidf_(v0[j]); v1[j] = v1[j] * sigmoidf_(v1[j]); }
;                         } else if (kind == K_GATE) {
; #pragma unroll
;                             for (int j = 0; j < 4; ++j) { v0[j] = sigmoidf_(v0[j]); v1[j] = sigmoidf_(v1[j]); }
;                         } else { v0 = v0 * sc; v1 = v1 * sc; }
;                         *(u32x4*)(d + 32 * bj) = pack8(v0, v1);
.LBB0_471:
	s_andn2_b64 vcc, exec, s[70:71]
	s_cbranch_vccnz .LBB0_473
	v_mul_f32_e32 v130, 0xbfb8aa3b, v17
	v_mul_f32_e32 v131, 0xbfb8aa3b, v18
	v_exp_f32_e32 v133, v130
	v_mul_f32_e32 v130, 0xbfb8aa3b, v22
	v_exp_f32_e32 v134, v131
	v_mul_f32_e32 v131, 0xbfb8aa3b, v23
	v_exp_f32_e32 v130, v130
	v_exp_f32_e32 v131, v131
	v_mul_f32_e32 v129, 0xbfb8aa3b, v16
	v_mul_f32_e32 v128, 0xbfb8aa3b, v20
	v_exp_f32_e32 v132, v129
	v_pk_add_f32 v[130:131], v[130:131], 1.0 op_sel_hi:[1,0]
	v_mul_f32_e32 v129, 0xbfb8aa3b, v21
	v_exp_f32_e32 v128, v128
	v_exp_f32_e32 v129, v129
	v_pk_add_f32 v[132:133], v[132:133], 1.0 op_sel_hi:[1,0]
	v_rcp_f32_e32 v131, v131
	v_pk_add_f32 v[128:129], v[128:129], 1.0 op_sel_hi:[1,0]
	v_rcp_f32_e32 v130, v130
	s_nop 0
	v_rcp_f32_e32 v129, v129
	s_nop 0
	v_rcp_f32_e32 v128, v128
	v_mul_f32_e32 v135, 0xbfb8aa3b, v19
	v_exp_f32_e32 v135, v135
	s_nop 0
	v_pk_add_f32 v[134:135], v[134:135], 1.0 op_sel_hi:[1,0]
	s_nop 0
	s_nop 0
	v_rcp_f32_e32 v135, v135
	s_nop 0
	v_rcp_f32_e32 v134, v134
	s_nop 0
	v_rcp_f32_e32 v133, v133
	s_nop 0
	v_rcp_f32_e32 v132, v132

; DI u32x4 pack8(f32x4 a, f32x4 b) { u32x4 w; w.x = pk2(a[0], a[1]); w.y = pk2(a[2], a[3]); w.z = pk2(b[0], b[1]); w.w = pk2(b[2], b[3]); return w; }
; DI float sigmoidf_(float v) { return __fdividef(1.f, 1.f + __expf(-v)); }
; template <int PH>
; DI void epilogue(const Params& p, const f32x4 (&acc)[2][2][4][2], const Unit& u, int wr, int wc, int fr, int fq) {
;     ...
;                     for (int bj = 0; bj < 2; ++bj) {
;                         f32x4 v0 = acc[ai][bj][m][0], v1 = acc[ai][bj][m][1];
;                         if (kind == K_SILU) {
; #pragma unroll
;                             for (int j = 0; j < 4; ++j) { v0[j] = v0[j] * sigmoidf_(v0[j]); v1[j] = v1[j] * sigmoidf_(v1[j]); }
;                         } else if (kind == K_GATE) {
; #pragma unroll
;                             for (int j = 0; j < 4; ++j) { v0[j] = sigmoidf_(v0[j]); v1[j] = sigmoidf_(v1[j]); }
;                         } else { v0 = v0 * sc; v1 = v1 * sc; }
;                         *(u32x4*)(d + 32 * bj) = pack8(v0, v1);
.LBB0_474:
	s_andn2_b64 vcc, exec, s[70:71]
	s_cbranch_vccnz .LBB0_476
	v_mul_f32_e32 v129, 0xbfb8aa3b, v16
	v_mul_f32_e32 v128, 0xbfb8aa3b, v20
	v_exp_f32_e32 v132, v129
	v_mul_f32_e32 v129, 0xbfb8aa3b, v21
	v_exp_f32_e32 v128, v128
	v_exp_f32_e32 v129, v129
	v_mul_f32_e32 v130, 0xbfb8aa3b, v17
	v_mul_f32_e32 v131, 0xbfb8aa3b, v18
	v_exp_f32_e32 v133, v130
	v_pk_add_f32 v[128:129], v[128:129], 1.0 op_sel_hi:[1,0]
	v_mul_f32_e32 v130, 0xbfb8aa3b, v22
	v_exp_f32_e32 v134, v131
	v_mul_f32_e32 v131, 0xbfb8aa3b, v23
	v_exp_f32_e32 v130, v130
	v_rcp_f32_e32 v129, v129
	v_exp_f32_e32 v131, v131
	v_pk_add_f32 v[132:133], v[132:133], 1.0 op_sel_hi:[1,0]
	v_pk_add_f32 v[130:131], v[130:131], 1.0 op_sel_hi:[1,0]
	v_rcp_f32_e32 v128, v128
	s_nop 0
	v_pk_mul_f32 v[128:129], v[20:21], v[128:129]
	v_rcp_f32_e32 v131, v131
	s_nop 0
	v_rcp_f32_e32 v130, v130
	v_mul_f32_e32 v135, 0xbfb8aa3b, v19
	v_exp_f32_e32 v135, v135
	v_rcp_f32_e32 v133, v133
	v_pk_add_f32 v[134:135], v[134:135], 1.0 op_sel_hi:[1,0]
	v_pk_mul_f32 v[130:131], v[22:23], v[130:131]
	v_rcp_f32_e32 v132, v132
	s_nop 0
	v_pk_mul_f32 v[132:133], v[16:17], v[132:133]
	v_rcp_f32_e32 v135, v135
	s_nop 0
	v_rcp_f32_e32 v134, v134
	s_nop 0
	v_pk_mul_f32 v[134:135], v[18:19], v[134:135]

; DI u32x4 pack8(f32x4 a, f32x4 b) { u32x4 w; w.x = pk2(a[0], a[1]); w.y = pk2(a[2], a[3]); w.z = pk2(b[0], b[1]); w.w = pk2(b[2], b[3]); return w; }
; DI float sigmoidf_(float v) { return __fdividef(1.f, 1.f + __expf(-v)); }
; template <int PH>
; DI void epilogue(const Params& p, const f32x4 (&acc)[2][2][4][2], const Unit& u, int wr, int wc, int fr, int fq) {
;     ...
;                     for (int bj = 0; bj < 2; ++bj) {
;                         f32x4 v0 = acc[ai][bj][m][0], v1 = acc[ai][bj][m][1];
;                         if (kind == K_SILU) {
; #pragma unroll
;                             for (int j = 0; j < 4; ++j) { v0[j] = v0[j] * sigmoidf_(v0[j]); v1[j] = v1[j] * sigmoidf_(v1[j]); }
;                         } else if (kind == K_GATE) {
; #pragma unroll
;                             for (int j = 0; j < 4; ++j) { v0[j] = sigmoidf_(v0[j]); v1[j] = sigmoidf_(v1[j]); }
;                         } else { v0 = v0 * sc; v1 = v1 * sc; }
;                         *(u32x4*)(d + 32 * bj) = pack8(v0, v1);
.LBB0_479:
	s_andn2_b64 vcc, exec, s[70:71]
	s_cbranch_vccnz .LBB0_481
	v_mul_f32_e32 v130, 0xbfb8aa3b, v41
	v_mul_f32_e32 v131, 0xbfb8aa3b, v42
	v_exp_f32_e32 v133, v130
	v_mul_f32_e32 v130, 0xbfb8aa3b, v46
	v_exp_f32_e32 v134, v131
	v_mul_f32_e32 v131, 0xbfb8aa3b, v47
	v_exp_f32_e32 v130, v130
	v_exp_f32_e32 v131, v131
	v_mul_f32_e32 v129, 0xbfb8aa3b, v40
	v_mul_f32_e32 v128, 0xbfb8aa3b, v44
	v_exp_f32_e32 v132, v129
	v_pk_add_f32 v[130:131], v[130:131], 1.0 op_sel_hi:[1,0]
	v_mul_f32_e32 v129, 0xbfb8aa3b, v45
	v_exp_f32_e32 v128, v128
	v_exp_f32_e32 v129, v129
	v_pk_add_f32 v[132:133], v[132:133], 1.0 op_sel_hi:[1,0]
	v_rcp_f32_e32 v131, v131
	v_pk_add_f32 v[128:129], v[128:129], 1.0 op_sel_hi:[1,0]
	v_rcp_f32_e32 v130, v130
	s_nop 0
	v_rcp_f32_e32 v129, v129
	s_nop 0
	v_rcp_f32_e32 v128, v128
	v_mul_f32_e32 v135, 0xbfb8aa3b, v43
	v_exp_f32_e32 v135, v135
	s_nop 0
	v_pk_add_f32 v[134:135], v[134:135], 1.0 op_sel_hi:[1,0]
	s_nop 0
	s_nop 0
	v_rcp_f32_e32 v135, v135
	s_nop 0
	v_rcp_f32_e32 v134, v134
	s_nop 0
	v_rcp_f32_e32 v133, v133
	s_nop 0
	v_rcp_f32_e32 v132, v132

; DI u32x4 pack8(f32x4 a, f32x4 b) { u32x4 w; w.x = pk2(a[0], a[1]); w.y = pk2(a[2], a[3]); w.z = pk2(b[0], b[1]); w.w = pk2(b[2], b[3]); return w; }
; DI float sigmoidf_(float v) { return __fdividef(1.f, 1.f + __expf(-v)); }
; template <int PH>
; DI void epilogue(const Params& p, const f32x4 (&acc)[2][2][4][2], const Unit& u, int wr, int wc, int fr, int fq) {
;     ...
;                     for (int bj = 0; bj < 2; ++bj) {
;                         f32x4 v0 = acc[ai][bj][m][0], v1 = acc[ai][bj][m][1];
;                         if (kind == K_SILU) {
; #pragma unroll
;                             for (int j = 0; j < 4; ++j) { v0[j] = v0[j] * sigmoidf_(v0[j]); v1[j] = v1[j] * sigmoidf_(v1[j]); }
;                         } else if (kind == K_GATE) {
; #pragma unroll
;                             for (int j = 0; j < 4; ++j) { v0[j] = sigmoidf_(v0[j]); v1[j] = sigmoidf_(v1[j]); }
;                         } else { v0 = v0 * sc; v1 = v1 * sc; }
;                         *(u32x4*)(d + 32 * bj) = pack8(v0, v1);
.LBB0_482:
	s_andn2_b64 vcc, exec, s[70:71]
	s_cbranch_vccnz .LBB0_484
	v_mul_f32_e32 v129, 0xbfb8aa3b, v40
	v_mul_f32_e32 v128, 0xbfb8aa3b, v44
	v_exp_f32_e32 v132, v129
	v_mul_f32_e32 v129, 0xbfb8aa3b, v45
	v_exp_f32_e32 v128, v128
	v_exp_f32_e32 v129, v129
	v_mul_f32_e32 v130, 0xbfb8aa3b, v41
	v_mul_f32_e32 v131, 0xbfb8aa3b, v42
	v_exp_f32_e32 v133, v130
	v_pk_add_f32 v[128:129], v[128:129], 1.0 op_sel_hi:[1,0]
	v_mul_f32_e32 v130, 0xbfb8aa3b, v46
	v_exp_f32_e32 v134, v131
	v_mul_f32_e32 v131, 0xbfb8aa3b, v47
	v_exp_f32_e32 v130, v130
	v_rcp_f32_e32 v129, v129
	v_exp_f32_e32 v131, v131
	v_pk_add_f32 v[132:133], v[132:133], 1.0 op_sel_hi:[1,0]
	v_pk_add_f32 v[130:131], v[130:131], 1.0 op_sel_hi:[1,0]
	v_rcp_f32_e32 v128, v128
	s_nop 0
	v_pk_mul_f32 v[128:129], v[44:45], v[128:129]
	v_rcp_f32_e32 v131, v131
	s_nop 0
	v_rcp_f32_e32 v130, v130
	v_mul_f32_e32 v135, 0xbfb8aa3b, v43
	v_exp_f32_e32 v135, v135
	v_rcp_f32_e32 v133, v133
	v_pk_add_f32 v[134:135], v[134:135], 1.0 op_sel_hi:[1,0]
	v_pk_mul_f32 v[130:131], v[46:47], v[130:131]
	v_rcp_f32_e32 v132, v132
	s_nop 0
	v_pk_mul_f32 v[132:133], v[40:41], v[132:133]
	v_rcp_f32_e32 v135, v135
	s_nop 0
	v_rcp_f32_e32 v134, v134
	s_nop 0
	v_pk_mul_f32 v[134:135], v[42:43], v[134:135]

; DI u32x4 pack8(f32x4 a, f32x4 b) { u32x4 w; w.x = pk2(a[0], a[1]); w.y = pk2(a[2], a[3]); w.z = pk2(b[0], b[1]); w.w = pk2(b[2], b[3]); return w; }
; DI float sigmoidf_(float v) { return __fdividef(1.f, 1.f + __expf(-v)); }
; template <int PH>
; DI void epilogue(const Params& p, const f32x4 (&acc)[2][2][4][2], const Unit& u, int wr, int wc, int fr, int fq) {
;     ...
;                     for (int bj = 0; bj < 2; ++bj) {
;                         f32x4 v0 = acc[ai][bj][m][0], v1 = acc[ai][bj][m][1];
;                         if (kind == K_SILU) {
; #pragma unroll
;                             for (int j = 0; j < 4; ++j) { v0[j] = v0[j] * sigmoidf_(v0[j]); v1[j] = v1[j] * sigmoidf_(v1[j]); }
;                         } else if (kind == K_GATE) {
; #pragma unroll
;                             for (int j = 0; j < 4; ++j) { v0[j] = sigmoidf_(v0[j]); v1[j] = sigmoidf_(v1[j]); }
;                         } else { v0 = v0 * sc; v1 = v1 * sc; }
;                         *(u32x4*)(d + 32 * bj) = pack8(v0, v1);
.LBB0_487:
	s_andn2_b64 vcc, exec, s[70:71]
	s_cbranch_vccnz .LBB0_489
	v_mul_f32_e32 v130, 0xbfb8aa3b, v9
	v_mul_f32_e32 v131, 0xbfb8aa3b, v10
	v_exp_f32_e32 v133, v130
	v_mul_f32_e32 v130, 0xbfb8aa3b, v14
	v_exp_f32_e32 v134, v131
	v_mul_f32_e32 v131, 0xbfb8aa3b, v15
	v_exp_f32_e32 v130, v130
	v_exp_f32_e32 v131, v131
	v_mul_f32_e32 v129, 0xbfb8aa3b, v8
	v_mul_f32_e32 v128, 0xbfb8aa3b, v12
	v_exp_f32_e32 v132, v129
	v_pk_add_f32 v[130:131], v[130:131], 1.0 op_sel_hi:[1,0]
	v_mul_f32_e32 v129, 0xbfb8aa3b, v13
	v_exp_f32_e32 v128, v128
	v_exp_f32_e32 v129, v129
	v_pk_add_f32 v[132:133], v[132:133], 1.0 op_sel_hi:[1,0]
	v_rcp_f32_e32 v131, v131
	v_pk_add_f32 v[128:129], v[128:129], 1.0 op_sel_hi:[1,0]
	v_rcp_f32_e32 v130, v130
	s_nop 0
	v_rcp_f32_e32 v129, v129
	s_nop 0
	v_rcp_f32_e32 v128, v128
	v_mul_f32_e32 v135, 0xbfb8aa3b, v11
	v_exp_f32_e32 v135, v135
	s_nop 0
	v_pk_add_f32 v[134:135], v[134:135], 1.0 op_sel_hi:[1,0]
	s_nop 0
	s_nop 0
	v_rcp_f32_e32 v135, v135
	s_nop 0
	v_rcp_f32_e32 v134, v134
	s_nop 0
	v_rcp_f32_e32 v133, v133
	s_nop 0
	v_rcp_f32_e32 v132, v132

; DI u32x4 pack8(f32x4 a, f32x4 b) { u32x4 w; w.x = pk2(a[0], a[1]); w.y = pk2(a[2], a[3]); w.z = pk2(b[0], b[1]); w.w = pk2(b[2], b[3]); return w; }
; DI float sigmoidf_(float v) { return __fdividef(1.f, 1.f + __expf(-v)); }
; template <int PH>
; DI void epilogue(const Params& p, const f32x4 (&acc)[2][2][4][2], const Unit& u, int wr, int wc, int fr, int fq) {
;     ...
;                     for (int bj = 0; bj < 2; ++bj) {
;                         f32x4 v0 = acc[ai][bj][m][0], v1 = acc[ai][bj][m][1];
;                         if (kind == K_SILU) {
; #pragma unroll
;                             for (int j = 0; j < 4; ++j) { v0[j] = v0[j] * sigmoidf_(v0[j]); v1[j] = v1[j] * sigmoidf_(v1[j]); }
;                         } else if (kind == K_GATE) {
; #pragma unroll
;                             for (int j = 0; j < 4; ++j) { v0[j] = sigmoidf_(v0[j]); v1[j] = sigmoidf_(v1[j]); }
;                         } else { v0 = v0 * sc; v1 = v1 * sc; }
;                         *(u32x4*)(d + 32 * bj) = pack8(v0, v1);
.LBB0_490:
	s_andn2_b64 vcc, exec, s[70:71]
	s_cbranch_vccnz .LBB0_492
	v_mul_f32_e32 v129, 0xbfb8aa3b, v8
	v_mul_f32_e32 v128, 0xbfb8aa3b, v12
	v_exp_f32_e32 v132, v129
	v_mul_f32_e32 v129, 0xbfb8aa3b, v13
	v_exp_f32_e32 v128, v128
	v_exp_f32_e32 v129, v129
	v_mul_f32_e32 v130, 0xbfb8aa3b, v9
	v_mul_f32_e32 v131, 0xbfb8aa3b, v10
	v_exp_f32_e32 v133, v130
	v_pk_add_f32 v[128:129], v[128:129], 1.0 op_sel_hi:[1,0]
	v_mul_f32_e32 v130, 0xbfb8aa3b, v14
	v_exp_f32_e32 v134, v131
	v_mul_f32_e32 v131, 0xbfb8aa3b, v15
	v_exp_f32_e32 v130, v130
	v_rcp_f32_e32 v129, v129
	v_exp_f32_e32 v131, v131
	v_pk_add_f32 v[132:133], v[132:133], 1.0 op_sel_hi:[1,0]
	v_pk_add_f32 v[130:131], v[130:131], 1.0 op_sel_hi:[1,0]
	v_rcp_f32_e32 v128, v128
	s_nop 0
	v_pk_mul_f32 v[128:129], v[12:13], v[128:129]
	v_rcp_f32_e32 v131, v131
	s_nop 0
	v_rcp_f32_e32 v130, v130
	v_mul_f32_e32 v135, 0xbfb8aa3b, v11
	v_exp_f32_e32 v135, v135
	v_rcp_f32_e32 v133, v133
	v_pk_add_f32 v[134:135], v[134:135], 1.0 op_sel_hi:[1,0]
	v_pk_mul_f32 v[130:131], v[14:15], v[130:131]
	v_rcp_f32_e32 v132, v132
	s_nop 0
	v_pk_mul_f32 v[132:133], v[8:9], v[132:133]
	v_rcp_f32_e32 v135, v135
	s_nop 0
	v_rcp_f32_e32 v134, v134
	s_nop 0
	v_pk_mul_f32 v[134:135], v[10:11], v[134:135]

; DI u32x4 pack8(f32x4 a, f32x4 b) { u32x4 w; w.x = pk2(a[0], a[1]); w.y = pk2(a[2], a[3]); w.z = pk2(b[0], b[1]); w.w = pk2(b[2], b[3]); return w; }
; DI float sigmoidf_(float v) { return __fdividef(1.f, 1.f + __expf(-v)); }
; template <int PH>
; DI void epilogue(const Params& p, const f32x4 (&acc)[2][2][4][2], const Unit& u, int wr, int wc, int fr, int fq) {
;     ...
;                     for (int bj = 0; bj < 2; ++bj) {
;                         f32x4 v0 = acc[ai][bj][m][0], v1 = acc[ai][bj][m][1];
;                         if (kind == K_SILU) {
; #pragma unroll
;                             for (int j = 0; j < 4; ++j) { v0[j] = v0[j] * sigmoidf_(v0[j]); v1[j] = v1[j] * sigmoidf_(v1[j]); }
;                         } else if (kind == K_GATE) {
; #pragma unroll
;                             for (int j = 0; j < 4; ++j) { v0[j] = sigmoidf_(v0[j]); v1[j] = sigmoidf_(v1[j]); }
;                         } else { v0 = v0 * sc; v1 = v1 * sc; }
;                         *(u32x4*)(d + 32 * bj) = pack8(v0, v1);
.LBB0_495:
	s_andn2_b64 vcc, exec, s[70:71]
	s_cbranch_vccnz .LBB0_497
	v_mul_f32_e32 v130, 0xbfb8aa3b, v33
	v_mul_f32_e32 v131, 0xbfb8aa3b, v34
	v_exp_f32_e32 v133, v130
	v_mul_f32_e32 v130, 0xbfb8aa3b, v38
	v_exp_f32_e32 v134, v131
	v_mul_f32_e32 v131, 0xbfb8aa3b, v39
	v_exp_f32_e32 v130, v130
	v_exp_f32_e32 v131, v131
	v_mul_f32_e32 v129, 0xbfb8aa3b, v32
	v_mul_f32_e32 v128, 0xbfb8aa3b, v36
	v_exp_f32_e32 v132, v129
	v_pk_add_f32 v[130:131], v[130:131], 1.0 op_sel_hi:[1,0]
	v_mul_f32_e32 v129, 0xbfb8aa3b, v37
	v_exp_f32_e32 v128, v128
	v_exp_f32_e32 v129, v129
	v_pk_add_f32 v[132:133], v[132:133], 1.0 op_sel_hi:[1,0]
	v_rcp_f32_e32 v131, v131
	v_pk_add_f32 v[128:129], v[128:129], 1.0 op_sel_hi:[1,0]
	v_rcp_f32_e32 v130, v130
	s_nop 0
	v_rcp_f32_e32 v129, v129
	s_nop 0
	v_rcp_f32_e32 v128, v128
	v_mul_f32_e32 v135, 0xbfb8aa3b, v35
	v_exp_f32_e32 v135, v135
	s_nop 0
	v_pk_add_f32 v[134:135], v[134:135], 1.0 op_sel_hi:[1,0]
	s_nop 0
	s_nop 0
	v_rcp_f32_e32 v135, v135
	s_nop 0
	v_rcp_f32_e32 v134, v134
	s_nop 0
	v_rcp_f32_e32 v133, v133
	s_nop 0
	v_rcp_f32_e32 v132, v132

; DI u32x4 pack8(f32x4 a, f32x4 b) { u32x4 w; w.x = pk2(a[0], a[1]); w.y = pk2(a[2], a[3]); w.z = pk2(b[0], b[1]); w.w = pk2(b[2], b[3]); return w; }
; DI float sigmoidf_(float v) { return __fdividef(1.f, 1.f + __expf(-v)); }
; template <int PH>
; DI void epilogue(const Params& p, const f32x4 (&acc)[2][2][4][2], const Unit& u, int wr, int wc, int fr, int fq) {
;     ...
;                     for (int bj = 0; bj < 2; ++bj) {
;                         f32x4 v0 = acc[ai][bj][m][0], v1 = acc[ai][bj][m][1];
;                         if (kind == K_SILU) {
; #pragma unroll
;                             for (int j = 0; j < 4; ++j) { v0[j] = v0[j] * sigmoidf_(v0[j]); v1[j] = v1[j] * sigmoidf_(v1[j]); }
;                         } else if (kind == K_GATE) {
; #pragma unroll
;                             for (int j = 0; j < 4; ++j) { v0[j] = sigmoidf_(v0[j]); v1[j] = sigmoidf_(v1[j]); }
;                         } else { v0 = v0 * sc; v1 = v1 * sc; }
;                         *(u32x4*)(d + 32 * bj) = pack8(v0, v1);
.LBB0_498:
	s_andn2_b64 vcc, exec, s[70:71]
	s_cbranch_vccnz .LBB0_500
	v_mul_f32_e32 v129, 0xbfb8aa3b, v32
	v_mul_f32_e32 v128, 0xbfb8aa3b, v36
	v_exp_f32_e32 v132, v129
	v_mul_f32_e32 v129, 0xbfb8aa3b, v37
	v_exp_f32_e32 v128, v128
	v_exp_f32_e32 v129, v129
	v_mul_f32_e32 v130, 0xbfb8aa3b, v33
	v_mul_f32_e32 v131, 0xbfb8aa3b, v34
	v_exp_f32_e32 v133, v130
	v_pk_add_f32 v[128:129], v[128:129], 1.0 op_sel_hi:[1,0]
	v_mul_f32_e32 v130, 0xbfb8aa3b, v38
	v_exp_f32_e32 v134, v131
	v_mul_f32_e32 v131, 0xbfb8aa3b, v39
	v_exp_f32_e32 v130, v130
	v_rcp_f32_e32 v129, v129
	v_exp_f32_e32 v131, v131
	v_pk_add_f32 v[132:133], v[132:133], 1.0 op_sel_hi:[1,0]
	v_pk_add_f32 v[130:131], v[130:131], 1.0 op_sel_hi:[1,0]
	v_rcp_f32_e32 v128, v128
	s_nop 0
	v_pk_mul_f32 v[128:129], v[36:37], v[128:129]
	v_rcp_f32_e32 v131, v131
	s_nop 0
	v_rcp_f32_e32 v130, v130
	v_mul_f32_e32 v135, 0xbfb8aa3b, v35
	v_exp_f32_e32 v135, v135
	v_rcp_f32_e32 v133, v133
	v_pk_add_f32 v[134:135], v[134:135], 1.0 op_sel_hi:[1,0]
	v_pk_mul_f32 v[130:131], v[38:39], v[130:131]
	v_rcp_f32_e32 v132, v132
	s_nop 0
	v_pk_mul_f32 v[132:133], v[32:33], v[132:133]
	v_rcp_f32_e32 v135, v135
	s_nop 0
	v_rcp_f32_e32 v134, v134
	s_nop 0
	v_pk_mul_f32 v[134:135], v[34:35], v[134:135]

; DI u32x4 pack8(f32x4 a, f32x4 b) { u32x4 w; w.x = pk2(a[0], a[1]); w.y = pk2(a[2], a[3]); w.z = pk2(b[0], b[1]); w.w = pk2(b[2], b[3]); return w; }
; DI float sigmoidf_(float v) { return __fdividef(1.f, 1.f + __expf(-v)); }
; template <int PH>
; DI void epilogue(const Params& p, const f32x4 (&acc)[2][2][4][2], const Unit& u, int wr, int wc, int fr, int fq) {
;     ...
;                     for (int bj = 0; bj < 2; ++bj) {
;                         f32x4 v0 = acc[ai][bj][m][0], v1 = acc[ai][bj][m][1];
;                         if (kind == K_SILU) {
; #pragma unroll
;                             for (int j = 0; j < 4; ++j) { v0[j] = v0[j] * sigmoidf_(v0[j]); v1[j] = v1[j] * sigmoidf_(v1[j]); }
;                         } else if (kind == K_GATE) {
; #pragma unroll
;                             for (int j = 0; j < 4; ++j) { v0[j] = sigmoidf_(v0[j]); v1[j] = sigmoidf_(v1[j]); }
;                         } else { v0 = v0 * sc; v1 = v1 * sc; }
;                         *(u32x4*)(d + 32 * bj) = pack8(v0, v1);
.LBB0_503:
	s_andn2_b64 vcc, exec, s[4:5]
	s_cbranch_vccnz .LBB0_505
	v_mul_f32_e32 v130, 0xbfb8aa3b, v1
	v_mul_f32_e32 v131, 0xbfb8aa3b, v2
	v_exp_f32_e32 v133, v130
	v_mul_f32_e32 v130, 0xbfb8aa3b, v6
	v_exp_f32_e32 v134, v131
	v_mul_f32_e32 v131, 0xbfb8aa3b, v7
	v_exp_f32_e32 v130, v130
	v_exp_f32_e32 v131, v131
	v_mul_f32_e32 v129, 0xbfb8aa3b, v0
	v_mul_f32_e32 v128, 0xbfb8aa3b, v4
	v_exp_f32_e32 v132, v129
	v_pk_add_f32 v[130:131], v[130:131], 1.0 op_sel_hi:[1,0]
	v_mul_f32_e32 v129, 0xbfb8aa3b, v5
	v_exp_f32_e32 v128, v128
	v_exp_f32_e32 v129, v129
	v_pk_add_f32 v[132:133], v[132:133], 1.0 op_sel_hi:[1,0]
	v_rcp_f32_e32 v131, v131
	v_pk_add_f32 v[128:129], v[128:129], 1.0 op_sel_hi:[1,0]
	v_rcp_f32_e32 v130, v130
	s_nop 0
	v_rcp_f32_e32 v129, v129
	s_nop 0
	v_rcp_f32_e32 v128, v128
	v_mul_f32_e32 v135, 0xbfb8aa3b, v3
	v_exp_f32_e32 v135, v135
	s_nop 0
	v_pk_add_f32 v[134:135], v[134:135], 1.0 op_sel_hi:[1,0]
	s_nop 0
	s_nop 0
	v_rcp_f32_e32 v135, v135
	s_nop 0
	v_rcp_f32_e32 v134, v134
	s_nop 0
	v_rcp_f32_e32 v133, v133
	s_nop 0
	v_rcp_f32_e32 v132, v132

; DI u32x4 pack8(f32x4 a, f32x4 b) { u32x4 w; w.x = pk2(a[0], a[1]); w.y = pk2(a[2], a[3]); w.z = pk2(b[0], b[1]); w.w = pk2(b[2], b[3]); return w; }
; DI float sigmoidf_(float v) { return __fdividef(1.f, 1.f + __expf(-v)); }
; template <int PH>
; DI void epilogue(const Params& p, const f32x4 (&acc)[2][2][4][2], const Unit& u, int wr, int wc, int fr, int fq) {
;     ...
;                     for (int bj = 0; bj < 2; ++bj) {
;                         f32x4 v0 = acc[ai][bj][m][0], v1 = acc[ai][bj][m][1];
;                         if (kind == K_SILU) {
; #pragma unroll
;                             for (int j = 0; j < 4; ++j) { v0[j] = v0[j] * sigmoidf_(v0[j]); v1[j] = v1[j] * sigmoidf_(v1[j]); }
;                         } else if (kind == K_GATE) {
; #pragma unroll
;                             for (int j = 0; j < 4; ++j) { v0[j] = sigmoidf_(v0[j]); v1[j] = sigmoidf_(v1[j]); }
;                         } else { v0 = v0 * sc; v1 = v1 * sc; }
;                         *(u32x4*)(d + 32 * bj) = pack8(v0, v1);
.LBB0_506:
	s_andn2_b64 vcc, exec, s[6:7]
	s_cbranch_vccnz .LBB0_508
	v_mul_f32_e32 v129, 0xbfb8aa3b, v0
	v_mul_f32_e32 v128, 0xbfb8aa3b, v4
	v_exp_f32_e32 v132, v129
	v_mul_f32_e32 v129, 0xbfb8aa3b, v5
	v_exp_f32_e32 v128, v128
	v_exp_f32_e32 v129, v129
	v_mul_f32_e32 v130, 0xbfb8aa3b, v1
	v_mul_f32_e32 v131, 0xbfb8aa3b, v2
	v_exp_f32_e32 v133, v130
	v_pk_add_f32 v[128:129], v[128:129], 1.0 op_sel_hi:[1,0]
	v_mul_f32_e32 v130, 0xbfb8aa3b, v6
	v_exp_f32_e32 v134, v131
	v_mul_f32_e32 v131, 0xbfb8aa3b, v7
	v_exp_f32_e32 v130, v130
	v_rcp_f32_e32 v129, v129
	v_exp_f32_e32 v131, v131
	v_pk_add_f32 v[132:133], v[132:133], 1.0 op_sel_hi:[1,0]
	v_pk_add_f32 v[130:131], v[130:131], 1.0 op_sel_hi:[1,0]
	v_rcp_f32_e32 v128, v128
	s_nop 0
	v_pk_mul_f32 v[128:129], v[4:5], v[128:129]
	v_rcp_f32_e32 v131, v131
	s_nop 0
	v_rcp_f32_e32 v130, v130
	v_mul_f32_e32 v135, 0xbfb8aa3b, v3
	v_exp_f32_e32 v135, v135
	v_rcp_f32_e32 v133, v133
	v_pk_add_f32 v[134:135], v[134:135], 1.0 op_sel_hi:[1,0]
	v_pk_mul_f32 v[130:131], v[6:7], v[130:131]
	v_rcp_f32_e32 v132, v132
	s_nop 0
	v_pk_mul_f32 v[132:133], v[0:1], v[132:133]
	v_rcp_f32_e32 v135, v135
	s_nop 0
	v_rcp_f32_e32 v134, v134
	s_nop 0
	v_pk_mul_f32 v[134:135], v[2:3], v[134:135]

; DI u32x4 pack8(f32x4 a, f32x4 b) { u32x4 w; w.x = pk2(a[0], a[1]); w.y = pk2(a[2], a[3]); w.z = pk2(b[0], b[1]); w.w = pk2(b[2], b[3]); return w; }
; DI float sigmoidf_(float v) { return __fdividef(1.f, 1.f + __expf(-v)); }
; template <int PH>
; DI void epilogue(const Params& p, const f32x4 (&acc)[2][2][4][2], const Unit& u, int wr, int wc, int fr, int fq) {
;     ...
;             if (kind == K_GATE) {
; #pragma unroll
;                 for (int m = 0; m < 4; ++m) {
;                     const int r = u.pm * 256 + rl0 + 128 * ai + 16 * m;
;                     bf16_t* sg = (bf16_t*)(ws + OFF_SG) + (size_t)r * 1024 + u.coff + cl0;
; #pragma unroll
;                     for (int bj = 0; bj < 2; ++bj) {
;                         f32x4 v0 = acc[ai][bj][m][0], v1 = acc[ai][bj][m][1];
; #pragma unroll
;                         for (int j = 0; j < 4; ++j) { v0[j] = sigmoidf_(v0[j]); v1[j] = sigmoidf_(v1[j]); }
;                         *(u32x4*)(sg + 32 * bj) = pack8(v0, v1);
;                     }
.LBB0_1264:
	s_and_b64 vcc, exec, s[40:41]
	s_cbranch_vccz .LBB0_1266
	v_mul_f32_e32 v124, 0xbfb8aa3b, v124
	v_mul_f32_e32 v125, 0xbfb8aa3b, v125
	v_exp_f32_e32 v124, v124
	v_exp_f32_e32 v125, v125
	v_lshlrev_b64 v[128:129], 11, v[210:211]
	v_lshl_add_u64 v[128:129], s[20:21], 0, v[128:129]
	s_lshl_b64 s[40:41], s[10:11], 1
	v_pk_add_f32 v[130:131], v[124:125], 1.0 op_sel_hi:[1,0]
	v_lshl_add_u64 v[128:129], v[128:129], 0, s[40:41]
	v_lshl_add_u64 v[124:125], v[128:129], 0, v[196:197]
	v_mul_f32_e32 v120, 0xbfb8aa3b, v120
	v_mul_f32_e32 v121, 0xbfb8aa3b, v121
	v_exp_f32_e32 v120, v120
	v_exp_f32_e32 v121, v121
	v_rcp_f32_e32 v128, v131
	v_pk_add_f32 v[120:121], v[120:121], 1.0 op_sel_hi:[1,0]
	v_rcp_f32_e32 v129, v130
	v_mul_f32_e32 v126, 0xbfb8aa3b, v126
	v_rcp_f32_e32 v130, v121
	v_mul_f32_e32 v127, 0xbfb8aa3b, v127
	v_exp_f32_e32 v126, v126
	v_exp_f32_e32 v127, v127
	s_nop 0
	v_pk_add_f32 v[126:127], v[126:127], 1.0 op_sel_hi:[1,0]
	v_rcp_f32_e32 v133, v120
	v_mul_f32_e32 v120, 0xbfb8aa3b, v122
	v_exp_f32_e32 v120, v120
	v_rcp_f32_e32 v122, v127
	v_mul_f32_e32 v121, 0xbfb8aa3b, v123
	v_exp_f32_e32 v121, v121
	s_nop 0
	v_pk_add_f32 v[120:121], v[120:121], 1.0 op_sel_hi:[1,0]
	v_rcp_f32_e32 v123, v126
	v_mul_f32_e32 v116, 0xbfb8aa3b, v116
	v_rcp_f32_e32 v126, v121
	v_mul_f32_e32 v117, 0xbfb8aa3b, v117
	v_exp_f32_e32 v116, v116
	v_exp_f32_e32 v117, v117
	v_rcp_f32_e32 v127, v120
	v_pk_add_f32 v[116:117], v[116:117], 1.0 op_sel_hi:[1,0]
	v_cvt_pk_bf16_f32 v121, v123, v122
	v_cvt_pk_bf16_f32 v123, v127, v126
	v_cvt_pk_bf16_f32 v120, v129, v128
	v_cvt_pk_bf16_f32 v122, v133, v130
	global_store_dwordx4 v[124:125], v[120:123], off
	v_mul_f32_e32 v112, 0xbfb8aa3b, v112
	v_mul_f32_e32 v113, 0xbfb8aa3b, v113
	v_exp_f32_e32 v112, v112
	v_rcp_f32_e32 v120, v117
	v_exp_f32_e32 v113, v113
	s_nop 0
	v_pk_add_f32 v[112:113], v[112:113], 1.0 op_sel_hi:[1,0]
	v_rcp_f32_e32 v121, v116
	v_mul_f32_e32 v108, 0xbfb8aa3b, v108
	v_rcp_f32_e32 v126, v113
	v_mul_f32_e32 v117, 0xbfb8aa3b, v119
	v_mul_f32_e32 v116, 0xbfb8aa3b, v118
	v_exp_f32_e32 v116, v116
	v_exp_f32_e32 v117, v117
	v_rcp_f32_e32 v122, v112
	v_pk_add_f32 v[116:117], v[116:117], 1.0 op_sel_hi:[1,0]
	v_mul_f32_e32 v112, 0xbfb8aa3b, v114
	v_exp_f32_e32 v112, v112
	v_mul_f32_e32 v109, 0xbfb8aa3b, v109
	v_exp_f32_e32 v108, v108
	v_rcp_f32_e32 v114, v117
	v_mul_f32_e32 v113, 0xbfb8aa3b, v115
	v_exp_f32_e32 v113, v113
	s_nop 0
	v_pk_add_f32 v[112:113], v[112:113], 1.0 op_sel_hi:[1,0]
	v_rcp_f32_e32 v115, v116
	v_exp_f32_e32 v109, v109
	v_rcp_f32_e32 v116, v113
	v_mul_f32_e32 v104, 0xbfb8aa3b, v104
	v_rcp_f32_e32 v117, v112
	v_cvt_pk_bf16_f32 v112, v121, v120
	v_cvt_pk_bf16_f32 v113, v115, v114
	v_cvt_pk_bf16_f32 v114, v122, v126
	v_cvt_pk_bf16_f32 v115, v117, v116
	global_store_dwordx4 v[124:125], v[112:115], off offset:64
	v_mul_f32_e32 v105, 0xbfb8aa3b, v105
	v_exp_f32_e32 v104, v104
	v_pk_add_f32 v[114:115], v[108:109], 1.0 op_sel_hi:[1,0]
	v_add_u32_e32 v112, s42, v223
	v_ashrrev_i32_e32 v113, 31, v112
	v_lshlrev_b64 v[112:113], 11, v[112:113]
	v_lshl_add_u64 v[112:113], s[20:21], 0, v[112:113]
	v_lshl_add_u64 v[112:113], v[112:113], 0, s[40:41]
	v_lshl_add_u64 v[108:109], v[112:113], 0, v[196:197]
	v_exp_f32_e32 v105, v105
	v_rcp_f32_e32 v112, v115
	v_pk_add_f32 v[104:105], v[104:105], 1.0 op_sel_hi:[1,0]
	v_rcp_f32_e32 v113, v114
	v_mul_f32_e32 v110, 0xbfb8aa3b, v110
	v_rcp_f32_e32 v114, v105
	v_mul_f32_e32 v111, 0xbfb8aa3b, v111
	v_exp_f32_e32 v110, v110
	v_exp_f32_e32 v111, v111
	s_nop 0
	v_pk_add_f32 v[110:111], v[110:111], 1.0 op_sel_hi:[1,0]
	v_rcp_f32_e32 v117, v104
	v_mul_f32_e32 v104, 0xbfb8aa3b, v106
	v_exp_f32_e32 v104, v104
	v_rcp_f32_e32 v106, v111
	v_mul_f32_e32 v105, 0xbfb8aa3b, v107
	v_exp_f32_e32 v105, v105
	s_nop 0
	v_pk_add_f32 v[104:105], v[104:105], 1.0 op_sel_hi:[1,0]
	v_rcp_f32_e32 v107, v110
	v_mul_f32_e32 v100, 0xbfb8aa3b, v100
	v_rcp_f32_e32 v110, v105
	v_mul_f32_e32 v101, 0xbfb8aa3b, v101
	v_exp_f32_e32 v100, v100
	v_exp_f32_e32 v101, v101
	v_rcp_f32_e32 v111, v104
	v_pk_add_f32 v[100:101], v[100:101], 1.0 op_sel_hi:[1,0]
	v_cvt_pk_bf16_f32 v105, v107, v106
	v_cvt_pk_bf16_f32 v107, v111, v110
	v_cvt_pk_bf16_f32 v104, v113, v112
	v_cvt_pk_bf16_f32 v106, v117, v114
	global_store_dwordx4 v[108:109], v[104:107], off
	v_mul_f32_e32 v96, 0xbfb8aa3b, v96
	v_mul_f32_e32 v97, 0xbfb8aa3b, v97
	v_exp_f32_e32 v96, v96
	v_rcp_f32_e32 v104, v101
	v_exp_f32_e32 v97, v97
	s_nop 0
	v_pk_add_f32 v[96:97], v[96:97], 1.0 op_sel_hi:[1,0]
	v_rcp_f32_e32 v105, v100
	v_mul_f32_e32 v92, 0xbfb8aa3b, v92
	v_rcp_f32_e32 v110, v97
	v_mul_f32_e32 v101, 0xbfb8aa3b, v103
	v_mul_f32_e32 v100, 0xbfb8aa3b, v102
	v_exp_f32_e32 v100, v100
	v_exp_f32_e32 v101, v101
	v_rcp_f32_e32 v106, v96
	v_pk_add_f32 v[100:101], v[100:101], 1.0 op_sel_hi:[1,0]
	v_mul_f32_e32 v96, 0xbfb8aa3b, v98
	v_exp_f32_e32 v96, v96
	v_mul_f32_e32 v93, 0xbfb8aa3b, v93
	v_exp_f32_e32 v92, v92
	v_rcp_f32_e32 v98, v101
	v_mul_f32_e32 v97, 0xbfb8aa3b, v99
	v_exp_f32_e32 v97, v97
	s_nop 0
; DI u32x4 pack8(f32x4 a, f32x4 b) { u32x4 w; w.x = pk2(a[0], a[1]); w.y = pk2(a[2], a[3]); w.z = pk2(b[0], b[1]); w.w = pk2(b[2], b[3]); return w; }
; DI float sigmoidf_(float v) { return __fdividef(1.f, 1.f + __expf(-v)); }
; template <int PH>
; DI void epilogue(const Params& p, const f32x4 (&acc)[2][2][4][2], const Unit& u, int wr, int wc, int fr, int fq) {
;     ...
;             if (kind == K_GATE) {
; #pragma unroll
;                 for (int m = 0; m < 4; ++m) {
;                     const int r = u.pm * 256 + rl0 + 128 * ai + 16 * m;
;                     bf16_t* sg = (bf16_t*)(ws + OFF_SG) + (size_t)r * 1024 + u.coff + cl0;
; #pragma unroll
;                     for (int bj = 0; bj < 2; ++bj) {
;                         f32x4 v0 = acc[ai][bj][m][0], v1 = acc[ai][bj][m][1];
; #pragma unroll
;                         for (int j = 0; j < 4; ++j) { v0[j] = sigmoidf_(v0[j]); v1[j] = sigmoidf_(v1[j]); }
;                         *(u32x4*)(sg + 32 * bj) = pack8(v0, v1);
;                     }
	v_pk_add_f32 v[96:97], v[96:97], 1.0 op_sel_hi:[1,0]
	v_rcp_f32_e32 v99, v100
	v_exp_f32_e32 v93, v93
	v_rcp_f32_e32 v100, v97
	v_mul_f32_e32 v88, 0xbfb8aa3b, v88
	v_rcp_f32_e32 v101, v96
	v_cvt_pk_bf16_f32 v96, v105, v104
	v_cvt_pk_bf16_f32 v97, v99, v98
	v_cvt_pk_bf16_f32 v98, v106, v110
	v_cvt_pk_bf16_f32 v99, v101, v100
	global_store_dwordx4 v[108:109], v[96:99], off offset:64
	v_mul_f32_e32 v89, 0xbfb8aa3b, v89
	v_exp_f32_e32 v88, v88
	v_pk_add_f32 v[98:99], v[92:93], 1.0 op_sel_hi:[1,0]
	v_add_u32_e32 v96, s42, v224
	v_ashrrev_i32_e32 v97, 31, v96
	v_lshlrev_b64 v[96:97], 11, v[96:97]
	v_lshl_add_u64 v[96:97], s[20:21], 0, v[96:97]
	v_lshl_add_u64 v[96:97], v[96:97], 0, s[40:41]
	v_lshl_add_u64 v[92:93], v[96:97], 0, v[196:197]
	v_exp_f32_e32 v89, v89
	v_rcp_f32_e32 v96, v99
	v_pk_add_f32 v[88:89], v[88:89], 1.0 op_sel_hi:[1,0]
	v_rcp_f32_e32 v97, v98
	v_mul_f32_e32 v94, 0xbfb8aa3b, v94
	v_rcp_f32_e32 v98, v89
	v_mul_f32_e32 v95, 0xbfb8aa3b, v95
	v_exp_f32_e32 v94, v94
	v_exp_f32_e32 v95, v95
	s_nop 0
	v_pk_add_f32 v[94:95], v[94:95], 1.0 op_sel_hi:[1,0]
	v_rcp_f32_e32 v101, v88
	v_mul_f32_e32 v88, 0xbfb8aa3b, v90
	v_exp_f32_e32 v88, v88
	v_rcp_f32_e32 v90, v95
	v_mul_f32_e32 v89, 0xbfb8aa3b, v91
	v_exp_f32_e32 v89, v89
	s_nop 0
	v_pk_add_f32 v[88:89], v[88:89], 1.0 op_sel_hi:[1,0]
	v_rcp_f32_e32 v91, v94
	v_mul_f32_e32 v84, 0xbfb8aa3b, v84
	v_rcp_f32_e32 v94, v89
	v_mul_f32_e32 v85, 0xbfb8aa3b, v85
	v_exp_f32_e32 v84, v84
	v_exp_f32_e32 v85, v85
	v_rcp_f32_e32 v95, v88
	v_pk_add_f32 v[84:85], v[84:85], 1.0 op_sel_hi:[1,0]
	v_cvt_pk_bf16_f32 v89, v91, v90
	v_cvt_pk_bf16_f32 v91, v95, v94
	v_cvt_pk_bf16_f32 v88, v97, v96
	v_cvt_pk_bf16_f32 v90, v101, v98
	global_store_dwordx4 v[92:93], v[88:91], off
	v_mul_f32_e32 v80, 0xbfb8aa3b, v80
	v_mul_f32_e32 v81, 0xbfb8aa3b, v81
	v_exp_f32_e32 v80, v80
	v_rcp_f32_e32 v88, v85
	v_exp_f32_e32 v81, v81
	s_nop 0
	v_pk_add_f32 v[80:81], v[80:81], 1.0 op_sel_hi:[1,0]
	v_rcp_f32_e32 v89, v84
	v_mul_f32_e32 v76, 0xbfb8aa3b, v76
	v_rcp_f32_e32 v94, v81
	v_mul_f32_e32 v85, 0xbfb8aa3b, v87
	v_mul_f32_e32 v84, 0xbfb8aa3b, v86
	v_exp_f32_e32 v84, v84
	v_exp_f32_e32 v85, v85
	v_rcp_f32_e32 v90, v80
	v_pk_add_f32 v[84:85], v[84:85], 1.0 op_sel_hi:[1,0]
	v_mul_f32_e32 v80, 0xbfb8aa3b, v82
	v_exp_f32_e32 v80, v80
	v_mul_f32_e32 v77, 0xbfb8aa3b, v77
	v_exp_f32_e32 v76, v76
	v_rcp_f32_e32 v82, v85
	v_mul_f32_e32 v81, 0xbfb8aa3b, v83
	v_exp_f32_e32 v81, v81
	s_nop 0
	v_pk_add_f32 v[80:81], v[80:81], 1.0 op_sel_hi:[1,0]
	v_rcp_f32_e32 v83, v84
	v_exp_f32_e32 v77, v77
	v_rcp_f32_e32 v84, v81
	v_pk_add_f32 v[76:77], v[76:77], 1.0 op_sel_hi:[1,0]
	v_rcp_f32_e32 v85, v80
	v_cvt_pk_bf16_f32 v80, v89, v88
	v_cvt_pk_bf16_f32 v81, v83, v82
	v_cvt_pk_bf16_f32 v82, v90, v94
	v_cvt_pk_bf16_f32 v83, v85, v84
	global_store_dwordx4 v[92:93], v[80:83], off offset:64
	v_mul_f32_e32 v72, 0xbfb8aa3b, v72
	v_mul_f32_e32 v73, 0xbfb8aa3b, v73
	v_exp_f32_e32 v72, v72
	v_exp_f32_e32 v73, v73
	v_mul_f32_e32 v68, 0xbfb8aa3b, v68
	v_rcp_f32_e32 v82, v77
	v_pk_add_f32 v[72:73], v[72:73], 1.0 op_sel_hi:[1,0]
	v_rcp_f32_e32 v83, v76
	v_mul_f32_e32 v69, 0xbfb8aa3b, v69
	v_rcp_f32_e32 v85, v73
	v_mul_f32_e32 v77, 0xbfb8aa3b, v79
	v_mul_f32_e32 v76, 0xbfb8aa3b, v78
	v_exp_f32_e32 v76, v76
	v_exp_f32_e32 v77, v77
	v_rcp_f32_e32 v84, v72
	v_pk_add_f32 v[76:77], v[76:77], 1.0 op_sel_hi:[1,0]
	v_mul_f32_e32 v72, 0xbfb8aa3b, v74
	v_exp_f32_e32 v72, v72
	v_exp_f32_e32 v68, v68
	v_exp_f32_e32 v69, v69
	v_rcp_f32_e32 v74, v77
	v_mul_f32_e32 v73, 0xbfb8aa3b, v75
	v_exp_f32_e32 v73, v73
	s_nop 0
	v_pk_add_f32 v[72:73], v[72:73], 1.0 op_sel_hi:[1,0]
	v_rcp_f32_e32 v75, v76
	v_add_u32_e32 v80, s42, v225
	v_rcp_f32_e32 v76, v73
	v_pk_add_f32 v[68:69], v[68:69], 1.0 op_sel_hi:[1,0]
	v_rcp_f32_e32 v77, v72
	v_ashrrev_i32_e32 v81, 31, v80
	v_cvt_pk_bf16_f32 v73, v75, v74
	v_cvt_pk_bf16_f32 v75, v77, v76
	v_lshlrev_b64 v[80:81], 11, v[80:81]
	v_lshl_add_u64 v[164:165], s[20:21], 0, v[80:81]
	v_lshl_add_u64 v[80:81], v[164:165], 0, s[40:41]
	v_lshl_add_u64 v[80:81], v[80:81], 0, v[196:197]
	v_cvt_pk_bf16_f32 v72, v83, v82
	v_cvt_pk_bf16_f32 v74, v84, v85
	global_store_dwordx4 v[80:81], v[72:75], off
	v_mul_f32_e32 v64, 0xbfb8aa3b, v64
	v_mul_f32_e32 v65, 0xbfb8aa3b, v65
	v_exp_f32_e32 v64, v64
	v_rcp_f32_e32 v72, v69
	v_exp_f32_e32 v65, v65
	s_nop 0
	v_pk_add_f32 v[64:65], v[64:65], 1.0 op_sel_hi:[1,0]
	v_rcp_f32_e32 v73, v68
	s_nop 0
	v_cvt_pk_bf16_f32 v160, v73, v72
	v_rcp_f32_e32 v76, v65
	v_mul_f32_e32 v69, 0xbfb8aa3b, v71
	v_mul_f32_e32 v68, 0xbfb8aa3b, v70
	v_exp_f32_e32 v68, v68
	v_exp_f32_e32 v69, v69
	v_rcp_f32_e32 v74, v64
	v_pk_add_f32 v[68:69], v[68:69], 1.0 op_sel_hi:[1,0]
	v_mul_f32_e32 v64, 0xbfb8aa3b, v66
	v_exp_f32_e32 v64, v64
	v_cvt_pk_bf16_f32 v162, v74, v76
	v_rcp_f32_e32 v66, v69
	v_mul_f32_e32 v65, 0xbfb8aa3b, v67
	v_exp_f32_e32 v65, v65
	s_nop 0
	v_pk_add_f32 v[64:65], v[64:65], 1.0 op_sel_hi:[1,0]
	v_rcp_f32_e32 v67, v68
	s_nop 0
	v_cvt_pk_bf16_f32 v161, v67, v66
	v_rcp_f32_e32 v167, v65
	v_rcp_f32_e32 v166, v64

; DI u32x4 pack8(f32x4 a, f32x4 b) { u32x4 w; w.x = pk2(a[0], a[1]); w.y = pk2(a[2], a[3]); w.z = pk2(b[0], b[1]); w.w = pk2(b[2], b[3]); return w; }
; DI float sigmoidf_(float v) { return __fdividef(1.f, 1.f + __expf(-v)); }
; template <int PH>
; DI void epilogue(const Params& p, const f32x4 (&acc)[2][2][4][2], const Unit& u, int wr, int wc, int fr, int fq) {
;     ...
;             if (kind == K_GATE) {
; #pragma unroll
;                 for (int m = 0; m < 4; ++m) {
;                     const int r = u.pm * 256 + rl0 + 128 * ai + 16 * m;
;                     bf16_t* sg = (bf16_t*)(ws + OFF_SG) + (size_t)r * 1024 + u.coff + cl0;
; #pragma unroll
;                     for (int bj = 0; bj < 2; ++bj) {
;                         f32x4 v0 = acc[ai][bj][m][0], v1 = acc[ai][bj][m][1];
; #pragma unroll
;                         for (int j = 0; j < 4; ++j) { v0[j] = sigmoidf_(v0[j]); v1[j] = sigmoidf_(v1[j]); }
;                         *(u32x4*)(sg + 32 * bj) = pack8(v0, v1);
;                     }
.LBB0_1300:
	s_and_b64 vcc, exec, s[40:41]
	s_cbranch_vccz .LBB0_1302
	v_mul_f32_e32 v60, 0xbfb8aa3b, v60
	v_mul_f32_e32 v61, 0xbfb8aa3b, v61
	v_exp_f32_e32 v60, v60
	v_exp_f32_e32 v61, v61
	v_lshlrev_b64 v[64:65], 11, v[96:97]
	v_lshl_add_u64 v[64:65], s[20:21], 0, v[64:65]
	s_lshl_b64 s[6:7], s[10:11], 1
	v_pk_add_f32 v[66:67], v[60:61], 1.0 op_sel_hi:[1,0]
	v_lshl_add_u64 v[64:65], v[64:65], 0, s[6:7]
	v_lshl_add_u64 v[60:61], v[64:65], 0, v[196:197]
	v_mul_f32_e32 v56, 0xbfb8aa3b, v56
	v_mul_f32_e32 v57, 0xbfb8aa3b, v57
	v_exp_f32_e32 v56, v56
	v_exp_f32_e32 v57, v57
	v_rcp_f32_e32 v64, v67
	v_pk_add_f32 v[56:57], v[56:57], 1.0 op_sel_hi:[1,0]
	v_rcp_f32_e32 v65, v66
	v_mul_f32_e32 v62, 0xbfb8aa3b, v62
	v_rcp_f32_e32 v66, v57
	v_mul_f32_e32 v63, 0xbfb8aa3b, v63
	v_exp_f32_e32 v62, v62
	v_exp_f32_e32 v63, v63
	s_nop 0
	v_pk_add_f32 v[62:63], v[62:63], 1.0 op_sel_hi:[1,0]
	v_rcp_f32_e32 v69, v56
	v_mul_f32_e32 v56, 0xbfb8aa3b, v58
	v_exp_f32_e32 v56, v56
	v_rcp_f32_e32 v58, v63
	v_mul_f32_e32 v57, 0xbfb8aa3b, v59
	v_exp_f32_e32 v57, v57
	s_nop 0
	v_pk_add_f32 v[56:57], v[56:57], 1.0 op_sel_hi:[1,0]
	v_rcp_f32_e32 v59, v62
	v_mul_f32_e32 v52, 0xbfb8aa3b, v52
	v_rcp_f32_e32 v62, v57
	v_mul_f32_e32 v53, 0xbfb8aa3b, v53
	v_exp_f32_e32 v52, v52
	v_exp_f32_e32 v53, v53
	v_rcp_f32_e32 v63, v56
	v_pk_add_f32 v[52:53], v[52:53], 1.0 op_sel_hi:[1,0]
	v_cvt_pk_bf16_f32 v57, v59, v58
	v_cvt_pk_bf16_f32 v59, v63, v62
	v_cvt_pk_bf16_f32 v56, v65, v64
	v_cvt_pk_bf16_f32 v58, v69, v66
	global_store_dwordx4 v[60:61], v[56:59], off
	v_mul_f32_e32 v48, 0xbfb8aa3b, v48
	v_mul_f32_e32 v49, 0xbfb8aa3b, v49
	v_exp_f32_e32 v48, v48
	v_rcp_f32_e32 v56, v53
	v_exp_f32_e32 v49, v49
	s_nop 0
	v_pk_add_f32 v[48:49], v[48:49], 1.0 op_sel_hi:[1,0]
	v_rcp_f32_e32 v57, v52
	v_mul_f32_e32 v44, 0xbfb8aa3b, v44
	v_rcp_f32_e32 v62, v49
	v_mul_f32_e32 v53, 0xbfb8aa3b, v55
	v_mul_f32_e32 v52, 0xbfb8aa3b, v54
	v_exp_f32_e32 v52, v52
	v_exp_f32_e32 v53, v53
	v_rcp_f32_e32 v58, v48
	v_pk_add_f32 v[52:53], v[52:53], 1.0 op_sel_hi:[1,0]
	v_mul_f32_e32 v48, 0xbfb8aa3b, v50
	v_exp_f32_e32 v48, v48
	v_mul_f32_e32 v45, 0xbfb8aa3b, v45
	v_exp_f32_e32 v44, v44
	v_rcp_f32_e32 v50, v53
	v_mul_f32_e32 v49, 0xbfb8aa3b, v51
	v_exp_f32_e32 v49, v49
	s_nop 0
	v_pk_add_f32 v[48:49], v[48:49], 1.0 op_sel_hi:[1,0]
	v_rcp_f32_e32 v51, v52
	v_exp_f32_e32 v45, v45
	v_rcp_f32_e32 v52, v49
	v_mul_f32_e32 v40, 0xbfb8aa3b, v40
	v_rcp_f32_e32 v53, v48
	v_cvt_pk_bf16_f32 v48, v57, v56
	v_cvt_pk_bf16_f32 v49, v51, v50
	v_cvt_pk_bf16_f32 v50, v58, v62
	v_cvt_pk_bf16_f32 v51, v53, v52
	global_store_dwordx4 v[60:61], v[48:51], off offset:64
	v_mul_f32_e32 v41, 0xbfb8aa3b, v41
	v_exp_f32_e32 v40, v40
	v_pk_add_f32 v[50:51], v[44:45], 1.0 op_sel_hi:[1,0]
	v_add_u32_e32 v48, s42, v227
	v_ashrrev_i32_e32 v49, 31, v48
	v_lshlrev_b64 v[48:49], 11, v[48:49]
	v_lshl_add_u64 v[48:49], s[20:21], 0, v[48:49]
	v_lshl_add_u64 v[48:49], v[48:49], 0, s[6:7]
	v_lshl_add_u64 v[44:45], v[48:49], 0, v[196:197]
	v_exp_f32_e32 v41, v41
	v_rcp_f32_e32 v48, v51
	v_pk_add_f32 v[40:41], v[40:41], 1.0 op_sel_hi:[1,0]
	v_rcp_f32_e32 v49, v50
	v_mul_f32_e32 v46, 0xbfb8aa3b, v46
	v_rcp_f32_e32 v50, v41
	v_mul_f32_e32 v47, 0xbfb8aa3b, v47
	v_exp_f32_e32 v46, v46
	v_exp_f32_e32 v47, v47
	s_nop 0
	v_pk_add_f32 v[46:47], v[46:47], 1.0 op_sel_hi:[1,0]
	v_rcp_f32_e32 v53, v40
	v_mul_f32_e32 v40, 0xbfb8aa3b, v42
	v_exp_f32_e32 v40, v40
	v_rcp_f32_e32 v42, v47
	v_mul_f32_e32 v41, 0xbfb8aa3b, v43
	v_exp_f32_e32 v41, v41
	s_nop 0
	v_pk_add_f32 v[40:41], v[40:41], 1.0 op_sel_hi:[1,0]
	v_rcp_f32_e32 v43, v46
	v_mul_f32_e32 v36, 0xbfb8aa3b, v36
	v_rcp_f32_e32 v46, v41
	v_mul_f32_e32 v37, 0xbfb8aa3b, v37
	v_exp_f32_e32 v36, v36
	v_exp_f32_e32 v37, v37
	v_rcp_f32_e32 v47, v40
	v_pk_add_f32 v[36:37], v[36:37], 1.0 op_sel_hi:[1,0]
	v_cvt_pk_bf16_f32 v41, v43, v42
	v_cvt_pk_bf16_f32 v43, v47, v46
	v_cvt_pk_bf16_f32 v40, v49, v48
	v_cvt_pk_bf16_f32 v42, v53, v50
	global_store_dwordx4 v[44:45], v[40:43], off
	v_mul_f32_e32 v32, 0xbfb8aa3b, v32
	v_mul_f32_e32 v33, 0xbfb8aa3b, v33
	v_exp_f32_e32 v32, v32
	v_rcp_f32_e32 v40, v37
	v_exp_f32_e32 v33, v33
	s_nop 0
	v_pk_add_f32 v[32:33], v[32:33], 1.0 op_sel_hi:[1,0]
	v_rcp_f32_e32 v41, v36
	v_mul_f32_e32 v28, 0xbfb8aa3b, v28
	v_rcp_f32_e32 v46, v33
	v_mul_f32_e32 v37, 0xbfb8aa3b, v39
	v_mul_f32_e32 v36, 0xbfb8aa3b, v38
	v_exp_f32_e32 v36, v36
	v_exp_f32_e32 v37, v37
	v_rcp_f32_e32 v42, v32
	v_pk_add_f32 v[36:37], v[36:37], 1.0 op_sel_hi:[1,0]
	v_mul_f32_e32 v32, 0xbfb8aa3b, v34
	v_exp_f32_e32 v32, v32
	v_mul_f32_e32 v29, 0xbfb8aa3b, v29
	v_exp_f32_e32 v28, v28
	v_rcp_f32_e32 v34, v37
	v_mul_f32_e32 v33, 0xbfb8aa3b, v35
	v_exp_f32_e32 v33, v33
	s_nop 0
	v_pk_add_f32 v[32:33], v[32:33], 1.0 op_sel_hi:[1,0]
	v_rcp_f32_e32 v35, v36
	v_exp_f32_e32 v29, v29
; DI u32x4 pack8(f32x4 a, f32x4 b) { u32x4 w; w.x = pk2(a[0], a[1]); w.y = pk2(a[2], a[3]); w.z = pk2(b[0], b[1]); w.w = pk2(b[2], b[3]); return w; }
; DI float sigmoidf_(float v) { return __fdividef(1.f, 1.f + __expf(-v)); }
; template <int PH>
; DI void epilogue(const Params& p, const f32x4 (&acc)[2][2][4][2], const Unit& u, int wr, int wc, int fr, int fq) {
;     ...
;             if (kind == K_GATE) {
; #pragma unroll
;                 for (int m = 0; m < 4; ++m) {
;                     const int r = u.pm * 256 + rl0 + 128 * ai + 16 * m;
;                     bf16_t* sg = (bf16_t*)(ws + OFF_SG) + (size_t)r * 1024 + u.coff + cl0;
; #pragma unroll
;                     for (int bj = 0; bj < 2; ++bj) {
;                         f32x4 v0 = acc[ai][bj][m][0], v1 = acc[ai][bj][m][1];
; #pragma unroll
;                         for (int j = 0; j < 4; ++j) { v0[j] = sigmoidf_(v0[j]); v1[j] = sigmoidf_(v1[j]); }
;                         *(u32x4*)(sg + 32 * bj) = pack8(v0, v1);
;                     }
;                 }
	v_rcp_f32_e32 v36, v33
	v_mul_f32_e32 v24, 0xbfb8aa3b, v24
	v_rcp_f32_e32 v37, v32
	v_cvt_pk_bf16_f32 v32, v41, v40
	v_cvt_pk_bf16_f32 v33, v35, v34
	v_cvt_pk_bf16_f32 v34, v42, v46
	v_cvt_pk_bf16_f32 v35, v37, v36
	global_store_dwordx4 v[44:45], v[32:35], off offset:64
	v_mul_f32_e32 v25, 0xbfb8aa3b, v25
	v_exp_f32_e32 v24, v24
	v_pk_add_f32 v[34:35], v[28:29], 1.0 op_sel_hi:[1,0]
	v_add_u32_e32 v32, s42, v228
	v_ashrrev_i32_e32 v33, 31, v32
	v_lshlrev_b64 v[32:33], 11, v[32:33]
	v_lshl_add_u64 v[32:33], s[20:21], 0, v[32:33]
	v_lshl_add_u64 v[32:33], v[32:33], 0, s[6:7]
	v_lshl_add_u64 v[28:29], v[32:33], 0, v[196:197]
	v_exp_f32_e32 v25, v25
	v_rcp_f32_e32 v32, v35
	v_pk_add_f32 v[24:25], v[24:25], 1.0 op_sel_hi:[1,0]
	v_rcp_f32_e32 v33, v34
	v_mul_f32_e32 v30, 0xbfb8aa3b, v30
	v_rcp_f32_e32 v34, v25
	v_mul_f32_e32 v31, 0xbfb8aa3b, v31
	v_exp_f32_e32 v30, v30
	v_exp_f32_e32 v31, v31
	s_nop 0
	v_pk_add_f32 v[30:31], v[30:31], 1.0 op_sel_hi:[1,0]
	v_rcp_f32_e32 v37, v24
	v_mul_f32_e32 v24, 0xbfb8aa3b, v26
	v_exp_f32_e32 v24, v24
	v_rcp_f32_e32 v26, v31
	v_mul_f32_e32 v25, 0xbfb8aa3b, v27
	v_exp_f32_e32 v25, v25
	s_nop 0
	v_pk_add_f32 v[24:25], v[24:25], 1.0 op_sel_hi:[1,0]
	v_rcp_f32_e32 v27, v30
	v_mul_f32_e32 v20, 0xbfb8aa3b, v20
	v_rcp_f32_e32 v30, v25
	v_mul_f32_e32 v21, 0xbfb8aa3b, v21
	v_exp_f32_e32 v20, v20
	v_exp_f32_e32 v21, v21
	v_rcp_f32_e32 v31, v24
	v_pk_add_f32 v[20:21], v[20:21], 1.0 op_sel_hi:[1,0]
	v_cvt_pk_bf16_f32 v25, v27, v26
	v_cvt_pk_bf16_f32 v27, v31, v30
	v_cvt_pk_bf16_f32 v24, v33, v32
	v_cvt_pk_bf16_f32 v26, v37, v34
	global_store_dwordx4 v[28:29], v[24:27], off
	v_mul_f32_e32 v16, 0xbfb8aa3b, v16
	v_mul_f32_e32 v17, 0xbfb8aa3b, v17
	v_exp_f32_e32 v16, v16
	v_rcp_f32_e32 v24, v21
	v_exp_f32_e32 v17, v17
	s_nop 0
	v_pk_add_f32 v[16:17], v[16:17], 1.0 op_sel_hi:[1,0]
	v_rcp_f32_e32 v25, v20
	v_mul_f32_e32 v12, 0xbfb8aa3b, v12
	v_rcp_f32_e32 v30, v17
	v_mul_f32_e32 v21, 0xbfb8aa3b, v23
	v_mul_f32_e32 v20, 0xbfb8aa3b, v22
	v_exp_f32_e32 v20, v20
	v_exp_f32_e32 v21, v21
	v_rcp_f32_e32 v26, v16
	v_pk_add_f32 v[20:21], v[20:21], 1.0 op_sel_hi:[1,0]
	v_mul_f32_e32 v16, 0xbfb8aa3b, v18
	v_exp_f32_e32 v16, v16
	v_mul_f32_e32 v13, 0xbfb8aa3b, v13
	v_exp_f32_e32 v12, v12
	v_rcp_f32_e32 v18, v21
	v_mul_f32_e32 v17, 0xbfb8aa3b, v19
	v_exp_f32_e32 v17, v17
	s_nop 0
	v_pk_add_f32 v[16:17], v[16:17], 1.0 op_sel_hi:[1,0]
	v_rcp_f32_e32 v19, v20
	v_exp_f32_e32 v13, v13
	v_rcp_f32_e32 v20, v17
	v_pk_add_f32 v[12:13], v[12:13], 1.0 op_sel_hi:[1,0]
	v_rcp_f32_e32 v21, v16
	v_cvt_pk_bf16_f32 v16, v25, v24
	v_cvt_pk_bf16_f32 v17, v19, v18
	v_cvt_pk_bf16_f32 v18, v26, v30
	v_cvt_pk_bf16_f32 v19, v21, v20
	global_store_dwordx4 v[28:29], v[16:19], off offset:64
	v_mul_f32_e32 v8, 0xbfb8aa3b, v8
	v_mul_f32_e32 v9, 0xbfb8aa3b, v9
	v_add_u32_e32 v16, s42, v229
	v_ashrrev_i32_e32 v17, 31, v16
	v_lshlrev_b64 v[16:17], 11, v[16:17]
	v_lshl_add_u64 v[68:69], s[20:21], 0, v[16:17]
	v_lshl_add_u64 v[16:17], v[68:69], 0, s[6:7]
	v_exp_f32_e32 v8, v8
	v_exp_f32_e32 v9, v9
	v_mul_f32_e32 v4, 0xbfb8aa3b, v4
	v_rcp_f32_e32 v18, v13
	v_pk_add_f32 v[8:9], v[8:9], 1.0 op_sel_hi:[1,0]
	v_rcp_f32_e32 v19, v12
	v_mul_f32_e32 v5, 0xbfb8aa3b, v5
	v_rcp_f32_e32 v21, v9
	v_mul_f32_e32 v13, 0xbfb8aa3b, v15
	v_mul_f32_e32 v12, 0xbfb8aa3b, v14
	v_exp_f32_e32 v12, v12
	v_exp_f32_e32 v13, v13
	v_rcp_f32_e32 v20, v8
	v_pk_add_f32 v[12:13], v[12:13], 1.0 op_sel_hi:[1,0]
	v_mul_f32_e32 v8, 0xbfb8aa3b, v10
	v_exp_f32_e32 v8, v8
	v_exp_f32_e32 v4, v4
	v_exp_f32_e32 v5, v5
	v_rcp_f32_e32 v10, v13
	v_mul_f32_e32 v9, 0xbfb8aa3b, v11
	v_exp_f32_e32 v9, v9
	s_nop 0
	v_pk_add_f32 v[8:9], v[8:9], 1.0 op_sel_hi:[1,0]
	v_rcp_f32_e32 v11, v12
	v_pk_add_f32 v[4:5], v[4:5], 1.0 op_sel_hi:[1,0]
	v_rcp_f32_e32 v12, v9
	v_lshl_add_u64 v[16:17], v[16:17], 0, v[196:197]
	v_rcp_f32_e32 v13, v8
	v_cvt_pk_bf16_f32 v9, v11, v10
	v_cvt_pk_bf16_f32 v11, v13, v12
	v_cvt_pk_bf16_f32 v8, v19, v18
	v_cvt_pk_bf16_f32 v10, v20, v21
	global_store_dwordx4 v[16:17], v[8:11], off
	v_mul_f32_e32 v0, 0xbfb8aa3b, v0
	v_mul_f32_e32 v1, 0xbfb8aa3b, v1
	v_exp_f32_e32 v0, v0
	v_rcp_f32_e32 v8, v5
	v_exp_f32_e32 v1, v1
	s_nop 0
	v_pk_add_f32 v[0:1], v[0:1], 1.0 op_sel_hi:[1,0]
	v_rcp_f32_e32 v9, v4
	s_nop 0
	v_cvt_pk_bf16_f32 v64, v9, v8
	v_rcp_f32_e32 v12, v1
	v_mul_f32_e32 v5, 0xbfb8aa3b, v7
	v_mul_f32_e32 v4, 0xbfb8aa3b, v6
	v_exp_f32_e32 v4, v4
	v_exp_f32_e32 v5, v5
	v_rcp_f32_e32 v10, v0
	v_pk_add_f32 v[4:5], v[4:5], 1.0 op_sel_hi:[1,0]
	v_mul_f32_e32 v0, 0xbfb8aa3b, v2
	v_exp_f32_e32 v0, v0
	v_cvt_pk_bf16_f32 v66, v10, v12
	v_rcp_f32_e32 v2, v5
	v_mul_f32_e32 v1, 0xbfb8aa3b, v3
	v_exp_f32_e32 v1, v1
	s_nop 0
	v_pk_add_f32 v[0:1], v[0:1], 1.0 op_sel_hi:[1,0]
	v_rcp_f32_e32 v3, v4
	s_nop 0
	v_cvt_pk_bf16_f32 v65, v3, v2
	v_rcp_f32_e32 v71, v1
	v_rcp_f32_e32 v70, v0
